# scan body reads operands two steps ahead (3-set register ring, one wait per step) + packed scale/sum in attention softmax common path
# baseline (speedup 1.0000x reference)
.LBB0_65:
	s_bitcmp1_b32 s40, 0
	s_cselect_b32 s2, 0x5500, 0
	v_lshl_or_b32 v94, v93, 2, s2
	v_lshl_add_u32 v95, v0, 2, s2
	v_mov_b32_e32 v96, s2
	v_mul_u32_u24_e32 v46, 0x154, v93
	v_add_u32_e32 v47, v46, v96
	v_add_u32_e32 v46, v46, v95
	ds_read_b64 v[44:45], v47 offset:1344
	ds_read_b32 v48, v46 offset:1280
	ds_read_b128 v[110:113], v94
	ds_read_b128 v[126:129], v94 offset:1024
	ds_read_b128 v[114:117], v94 offset:256
	ds_read_b128 v[118:121], v94 offset:512
	ds_read_b128 v[122:125], v94 offset:768
	ds_read_b32 v130, v95 offset:1280
	ds_read_b128 v[134:137], v94 offset:1360
	ds_read_b128 v[150:153], v94 offset:2384
	ds_read_b128 v[138:141], v94 offset:1616
	ds_read_b128 v[142:145], v94 offset:1872
	ds_read_b128 v[146:149], v94 offset:2128
	ds_read_b32 v154, v95 offset:2640
	s_mov_b64 s[2:3], 0x100
	s_mov_b64 s[20:21], 0x800
	s_waitcnt lgkmcnt(6)
	v_pk_mul_f32 v[24:25], v[30:31], v[112:113]
	v_pk_mul_f32 v[26:27], v[30:31], v[128:129]
	v_pk_fma_f32 v[24:25], v[28:29], v[110:111], v[24:25]
	v_pk_fma_f32 v[26:27], v[28:29], v[126:127], v[26:27]
	ds_read_b128 v[50:53], v94 offset:2720
	v_add_f32_e32 v34, v24, v25
	v_add_f32_e32 v35, v26, v27
	ds_read_b128 v[98:101], v94 offset:3744
	v_add_f32_dpp v34, v34, v34 quad_perm:[1,0,3,2] row_mask:0xf bank_mask:0xf bound_ctrl:1
	v_add_f32_dpp v35, v35, v35 quad_perm:[1,0,3,2] row_mask:0xf bank_mask:0xf bound_ctrl:1
	ds_read_b128 v[54:57], v94 offset:2976
	v_add_f32_dpp v34, v34, v34 quad_perm:[2,3,0,1] row_mask:0xf bank_mask:0xf bound_ctrl:1
	v_add_f32_dpp v35, v35, v35 quad_perm:[2,3,0,1] row_mask:0xf bank_mask:0xf bound_ctrl:1
	ds_read_b128 v[58:61], v94 offset:3232
	v_add_f32_dpp v34, v34, v34 row_ror:4 row_mask:0xf bank_mask:0xf bound_ctrl:1
	v_add_f32_dpp v35, v35, v35 row_ror:4 row_mask:0xf bank_mask:0xf bound_ctrl:1
	ds_read_b128 v[62:65], v94 offset:3488
	v_add_f32_dpp v34, v34, v34 row_ror:8 row_mask:0xf bank_mask:0xf bound_ctrl:1
	v_add_f32_dpp v35, v35, v35 row_ror:8 row_mask:0xf bank_mask:0xf bound_ctrl:1
	v_pk_mul_f32 v[36:37], v[114:115], v[34:35] op_sel_hi:[1,0]
	v_pk_mul_f32 v[38:39], v[116:117], v[34:35] op_sel_hi:[1,0]
	v_pk_fma_f32 v[36:37], v[122:123], v[130:131], v[36:37] op_sel_hi:[1,0,1] neg_lo:[0,0,1] neg_hi:[0,0,1]
	v_pk_fma_f32 v[38:39], v[124:125], v[130:131], v[38:39] op_sel_hi:[1,0,1] neg_lo:[0,0,1] neg_hi:[0,0,1]
	v_cndmask_b32_e64 v42, 0, v34, s[30:31]
	v_pk_fma_f32 v[28:29], v[28:29], v[118:119], v[36:37]
	v_pk_fma_f32 v[30:31], v[30:31], v[120:121], v[38:39]
	v_cndmask_b32_e64 v43, 0, v35, s[30:31]
	ds_read_b32 v66, v95 offset:4000
	s_waitcnt lgkmcnt(6)
	v_pk_mul_f32 v[24:25], v[30:31], v[136:137]
	v_pk_mul_f32 v[26:27], v[30:31], v[152:153]
	v_pk_fma_f32 v[24:25], v[28:29], v[134:135], v[24:25]
	v_pk_fma_f32 v[26:27], v[28:29], v[150:151], v[26:27]
	ds_read_b128 v[110:113], v94 offset:4080
	v_add_f32_e32 v34, v24, v25
	v_add_f32_e32 v35, v26, v27
	ds_read_b128 v[126:129], v94 offset:5104
	v_add_f32_dpp v34, v34, v34 quad_perm:[1,0,3,2] row_mask:0xf bank_mask:0xf bound_ctrl:1
	v_add_f32_dpp v35, v35, v35 quad_perm:[1,0,3,2] row_mask:0xf bank_mask:0xf bound_ctrl:1
	ds_read_b128 v[114:117], v94 offset:4336
	v_add_f32_dpp v34, v34, v34 quad_perm:[2,3,0,1] row_mask:0xf bank_mask:0xf bound_ctrl:1
	v_add_f32_dpp v35, v35, v35 quad_perm:[2,3,0,1] row_mask:0xf bank_mask:0xf bound_ctrl:1
	ds_read_b128 v[118:121], v94 offset:4592
	v_add_f32_dpp v34, v34, v34 row_ror:4 row_mask:0xf bank_mask:0xf bound_ctrl:1
	v_add_f32_dpp v35, v35, v35 row_ror:4 row_mask:0xf bank_mask:0xf bound_ctrl:1
	ds_read_b128 v[122:125], v94 offset:4848
	v_add_f32_dpp v34, v34, v34 row_ror:8 row_mask:0xf bank_mask:0xf bound_ctrl:1
	v_add_f32_dpp v35, v35, v35 row_ror:8 row_mask:0xf bank_mask:0xf bound_ctrl:1
	v_pk_mul_f32 v[36:37], v[138:139], v[34:35] op_sel_hi:[1,0]
	v_pk_mul_f32 v[38:39], v[140:141], v[34:35] op_sel_hi:[1,0]
	v_pk_fma_f32 v[36:37], v[146:147], v[154:155], v[36:37] op_sel_hi:[1,0,1] neg_lo:[0,0,1] neg_hi:[0,0,1]
	v_pk_fma_f32 v[38:39], v[148:149], v[154:155], v[38:39] op_sel_hi:[1,0,1] neg_lo:[0,0,1] neg_hi:[0,0,1]
	v_cndmask_b32_e64 v42, v42, v34, s[70:71]
	v_pk_fma_f32 v[28:29], v[28:29], v[142:143], v[36:37]
	v_pk_fma_f32 v[30:31], v[30:31], v[144:145], v[38:39]
	v_cndmask_b32_e64 v43, v43, v35, s[70:71]
	ds_read_b32 v130, v95 offset:5360
	s_waitcnt lgkmcnt(6)
	v_pk_mul_f32 v[24:25], v[30:31], v[52:53]
	v_pk_mul_f32 v[26:27], v[30:31], v[100:101]
	v_pk_fma_f32 v[24:25], v[28:29], v[50:51], v[24:25]
	v_pk_fma_f32 v[26:27], v[28:29], v[98:99], v[26:27]
	ds_read_b128 v[134:137], v94 offset:5440
	v_add_f32_e32 v34, v24, v25
	v_add_f32_e32 v35, v26, v27
	ds_read_b128 v[150:153], v94 offset:6464
	v_add_f32_dpp v34, v34, v34 quad_perm:[1,0,3,2] row_mask:0xf bank_mask:0xf bound_ctrl:1
	v_add_f32_dpp v35, v35, v35 quad_perm:[1,0,3,2] row_mask:0xf bank_mask:0xf bound_ctrl:1
	ds_read_b128 v[138:141], v94 offset:5696
	v_add_f32_dpp v34, v34, v34 quad_perm:[2,3,0,1] row_mask:0xf bank_mask:0xf bound_ctrl:1
	v_add_f32_dpp v35, v35, v35 quad_perm:[2,3,0,1] row_mask:0xf bank_mask:0xf bound_ctrl:1
	ds_read_b128 v[142:145], v94 offset:5952
	v_add_f32_dpp v34, v34, v34 row_ror:4 row_mask:0xf bank_mask:0xf bound_ctrl:1
	v_add_f32_dpp v35, v35, v35 row_ror:4 row_mask:0xf bank_mask:0xf bound_ctrl:1
	ds_read_b128 v[146:149], v94 offset:6208
	v_add_f32_dpp v34, v34, v34 row_ror:8 row_mask:0xf bank_mask:0xf bound_ctrl:1
	v_add_f32_dpp v35, v35, v35 row_ror:8 row_mask:0xf bank_mask:0xf bound_ctrl:1
	v_pk_mul_f32 v[36:37], v[54:55], v[34:35] op_sel_hi:[1,0]
	v_pk_mul_f32 v[38:39], v[56:57], v[34:35] op_sel_hi:[1,0]
	v_pk_fma_f32 v[36:37], v[62:63], v[66:67], v[36:37] op_sel_hi:[1,0,1] neg_lo:[0,0,1] neg_hi:[0,0,1]
	v_pk_fma_f32 v[38:39], v[64:65], v[66:67], v[38:39] op_sel_hi:[1,0,1] neg_lo:[0,0,1] neg_hi:[0,0,1]
	v_cndmask_b32_e64 v42, v42, v34, s[72:73]
	v_pk_fma_f32 v[28:29], v[28:29], v[58:59], v[36:37]
	v_pk_fma_f32 v[30:31], v[30:31], v[60:61], v[38:39]
	v_cndmask_b32_e64 v43, v43, v35, s[72:73]
	ds_read_b32 v154, v95 offset:6720
	s_waitcnt lgkmcnt(6)
	v_pk_mul_f32 v[24:25], v[30:31], v[112:113]
	v_pk_mul_f32 v[26:27], v[30:31], v[128:129]
	v_pk_fma_f32 v[24:25], v[28:29], v[110:111], v[24:25]
	v_pk_fma_f32 v[26:27], v[28:29], v[126:127], v[26:27]
	ds_read_b128 v[50:53], v94 offset:6800
	v_add_f32_e32 v34, v24, v25
	v_add_f32_e32 v35, v26, v27
	ds_read_b128 v[98:101], v94 offset:7824
	v_add_f32_dpp v34, v34, v34 quad_perm:[1,0,3,2] row_mask:0xf bank_mask:0xf bound_ctrl:1
	v_add_f32_dpp v35, v35, v35 quad_perm:[1,0,3,2] row_mask:0xf bank_mask:0xf bound_ctrl:1
	ds_read_b128 v[54:57], v94 offset:7056
	v_add_f32_dpp v34, v34, v34 quad_perm:[2,3,0,1] row_mask:0xf bank_mask:0xf bound_ctrl:1
	v_add_f32_dpp v35, v35, v35 quad_perm:[2,3,0,1] row_mask:0xf bank_mask:0xf bound_ctrl:1
	ds_read_b128 v[58:61], v94 offset:7312
	v_add_f32_dpp v34, v34, v34 row_ror:4 row_mask:0xf bank_mask:0xf bound_ctrl:1
	v_add_f32_dpp v35, v35, v35 row_ror:4 row_mask:0xf bank_mask:0xf bound_ctrl:1
	ds_read_b128 v[62:65], v94 offset:7568
	v_add_f32_dpp v34, v34, v34 row_ror:8 row_mask:0xf bank_mask:0xf bound_ctrl:1
	v_add_f32_dpp v35, v35, v35 row_ror:8 row_mask:0xf bank_mask:0xf bound_ctrl:1
	v_pk_mul_f32 v[36:37], v[114:115], v[34:35] op_sel_hi:[1,0]
	v_pk_mul_f32 v[38:39], v[116:117], v[34:35] op_sel_hi:[1,0]
	v_pk_fma_f32 v[36:37], v[122:123], v[130:131], v[36:37] op_sel_hi:[1,0,1] neg_lo:[0,0,1] neg_hi:[0,0,1]
	v_pk_fma_f32 v[38:39], v[124:125], v[130:131], v[38:39] op_sel_hi:[1,0,1] neg_lo:[0,0,1] neg_hi:[0,0,1]
	v_cndmask_b32_e64 v42, v42, v34, s[74:75]
	v_pk_fma_f32 v[28:29], v[28:29], v[118:119], v[36:37]
	v_pk_fma_f32 v[30:31], v[30:31], v[120:121], v[38:39]
	v_cndmask_b32_e64 v43, v43, v35, s[74:75]
	ds_read_b32 v66, v95 offset:8080
	s_waitcnt lgkmcnt(6)
	v_pk_mul_f32 v[24:25], v[30:31], v[136:137]
	v_pk_mul_f32 v[26:27], v[30:31], v[152:153]
	v_pk_fma_f32 v[24:25], v[28:29], v[134:135], v[24:25]
	v_pk_fma_f32 v[26:27], v[28:29], v[150:151], v[26:27]
	ds_read_b128 v[110:113], v94 offset:8160
	v_add_f32_e32 v34, v24, v25
	v_add_f32_e32 v35, v26, v27
	ds_read_b128 v[126:129], v94 offset:9184
	v_add_f32_dpp v34, v34, v34 quad_perm:[1,0,3,2] row_mask:0xf bank_mask:0xf bound_ctrl:1
	v_add_f32_dpp v35, v35, v35 quad_perm:[1,0,3,2] row_mask:0xf bank_mask:0xf bound_ctrl:1
	ds_read_b128 v[114:117], v94 offset:8416
	v_add_f32_dpp v34, v34, v34 quad_perm:[2,3,0,1] row_mask:0xf bank_mask:0xf bound_ctrl:1
	v_add_f32_dpp v35, v35, v35 quad_perm:[2,3,0,1] row_mask:0xf bank_mask:0xf bound_ctrl:1
	ds_read_b128 v[118:121], v94 offset:8672
	v_add_f32_dpp v34, v34, v34 row_ror:4 row_mask:0xf bank_mask:0xf bound_ctrl:1
	v_add_f32_dpp v35, v35, v35 row_ror:4 row_mask:0xf bank_mask:0xf bound_ctrl:1
	ds_read_b128 v[122:125], v94 offset:8928
	v_add_f32_dpp v34, v34, v34 row_ror:8 row_mask:0xf bank_mask:0xf bound_ctrl:1
	v_add_f32_dpp v35, v35, v35 row_ror:8 row_mask:0xf bank_mask:0xf bound_ctrl:1
	v_pk_mul_f32 v[36:37], v[138:139], v[34:35] op_sel_hi:[1,0]
	v_pk_mul_f32 v[38:39], v[140:141], v[34:35] op_sel_hi:[1,0]
	v_pk_fma_f32 v[36:37], v[146:147], v[154:155], v[36:37] op_sel_hi:[1,0,1] neg_lo:[0,0,1] neg_hi:[0,0,1]
	v_pk_fma_f32 v[38:39], v[148:149], v[154:155], v[38:39] op_sel_hi:[1,0,1] neg_lo:[0,0,1] neg_hi:[0,0,1]
	v_cndmask_b32_e64 v42, v42, v34, s[82:83]
	v_pk_fma_f32 v[28:29], v[28:29], v[142:143], v[36:37]
	v_pk_fma_f32 v[30:31], v[30:31], v[144:145], v[38:39]
	v_cndmask_b32_e64 v43, v43, v35, s[82:83]
	ds_read_b32 v130, v95 offset:9440
	s_waitcnt lgkmcnt(6)
	v_pk_mul_f32 v[24:25], v[30:31], v[52:53]
	v_pk_mul_f32 v[26:27], v[30:31], v[100:101]
	v_pk_fma_f32 v[24:25], v[28:29], v[50:51], v[24:25]
	v_pk_fma_f32 v[26:27], v[28:29], v[98:99], v[26:27]
	ds_read_b128 v[134:137], v94 offset:9520
	v_add_f32_e32 v34, v24, v25
	v_add_f32_e32 v35, v26, v27
	ds_read_b128 v[150:153], v94 offset:10544
	v_add_f32_dpp v34, v34, v34 quad_perm:[1,0,3,2] row_mask:0xf bank_mask:0xf bound_ctrl:1
	v_add_f32_dpp v35, v35, v35 quad_perm:[1,0,3,2] row_mask:0xf bank_mask:0xf bound_ctrl:1
	ds_read_b128 v[138:141], v94 offset:9776
	v_add_f32_dpp v34, v34, v34 quad_perm:[2,3,0,1] row_mask:0xf bank_mask:0xf bound_ctrl:1
	v_add_f32_dpp v35, v35, v35 quad_perm:[2,3,0,1] row_mask:0xf bank_mask:0xf bound_ctrl:1
	ds_read_b128 v[142:145], v94 offset:10032
	v_add_f32_dpp v34, v34, v34 row_ror:4 row_mask:0xf bank_mask:0xf bound_ctrl:1
	v_add_f32_dpp v35, v35, v35 row_ror:4 row_mask:0xf bank_mask:0xf bound_ctrl:1
	ds_read_b128 v[146:149], v94 offset:10288
	v_add_f32_dpp v34, v34, v34 row_ror:8 row_mask:0xf bank_mask:0xf bound_ctrl:1
	v_add_f32_dpp v35, v35, v35 row_ror:8 row_mask:0xf bank_mask:0xf bound_ctrl:1
	v_pk_mul_f32 v[36:37], v[54:55], v[34:35] op_sel_hi:[1,0]
	v_pk_mul_f32 v[38:39], v[56:57], v[34:35] op_sel_hi:[1,0]
	v_pk_fma_f32 v[36:37], v[62:63], v[66:67], v[36:37] op_sel_hi:[1,0,1] neg_lo:[0,0,1] neg_hi:[0,0,1]
	v_pk_fma_f32 v[38:39], v[64:65], v[66:67], v[38:39] op_sel_hi:[1,0,1] neg_lo:[0,0,1] neg_hi:[0,0,1]
	v_cndmask_b32_e64 v42, v42, v34, s[48:49]
	v_pk_fma_f32 v[28:29], v[28:29], v[58:59], v[36:37]
	v_pk_fma_f32 v[30:31], v[30:31], v[60:61], v[38:39]
	v_cndmask_b32_e64 v43, v43, v35, s[48:49]
	ds_read_b32 v154, v95 offset:10800
	s_waitcnt lgkmcnt(6)
	v_pk_mul_f32 v[24:25], v[30:31], v[112:113]
	v_pk_mul_f32 v[26:27], v[30:31], v[128:129]
	v_pk_fma_f32 v[24:25], v[28:29], v[110:111], v[24:25]
	v_pk_fma_f32 v[26:27], v[28:29], v[126:127], v[26:27]
	ds_read_b128 v[50:53], v94 offset:10880
	v_add_f32_e32 v34, v24, v25
	v_add_f32_e32 v35, v26, v27
	ds_read_b128 v[98:101], v94 offset:11904
	v_add_f32_dpp v34, v34, v34 quad_perm:[1,0,3,2] row_mask:0xf bank_mask:0xf bound_ctrl:1
	v_add_f32_dpp v35, v35, v35 quad_perm:[1,0,3,2] row_mask:0xf bank_mask:0xf bound_ctrl:1
	ds_read_b128 v[54:57], v94 offset:11136
	v_add_f32_dpp v34, v34, v34 quad_perm:[2,3,0,1] row_mask:0xf bank_mask:0xf bound_ctrl:1
	v_add_f32_dpp v35, v35, v35 quad_perm:[2,3,0,1] row_mask:0xf bank_mask:0xf bound_ctrl:1
	ds_read_b128 v[58:61], v94 offset:11392
	v_add_f32_dpp v34, v34, v34 row_ror:4 row_mask:0xf bank_mask:0xf bound_ctrl:1
	v_add_f32_dpp v35, v35, v35 row_ror:4 row_mask:0xf bank_mask:0xf bound_ctrl:1
	ds_read_b128 v[62:65], v94 offset:11648
	v_add_f32_dpp v34, v34, v34 row_ror:8 row_mask:0xf bank_mask:0xf bound_ctrl:1
	v_add_f32_dpp v35, v35, v35 row_ror:8 row_mask:0xf bank_mask:0xf bound_ctrl:1
	v_pk_mul_f32 v[36:37], v[114:115], v[34:35] op_sel_hi:[1,0]
	v_pk_mul_f32 v[38:39], v[116:117], v[34:35] op_sel_hi:[1,0]
	v_pk_fma_f32 v[36:37], v[122:123], v[130:131], v[36:37] op_sel_hi:[1,0,1] neg_lo:[0,0,1] neg_hi:[0,0,1]
	v_pk_fma_f32 v[38:39], v[124:125], v[130:131], v[38:39] op_sel_hi:[1,0,1] neg_lo:[0,0,1] neg_hi:[0,0,1]
	v_cndmask_b32_e64 v42, v42, v34, s[38:39]
	v_pk_fma_f32 v[28:29], v[28:29], v[118:119], v[36:37]
	v_pk_fma_f32 v[30:31], v[30:31], v[120:121], v[38:39]
	v_cndmask_b32_e64 v43, v43, v35, s[38:39]
	ds_read_b32 v66, v95 offset:12160
	s_waitcnt lgkmcnt(6)
	v_pk_mul_f32 v[24:25], v[30:31], v[136:137]
	v_pk_mul_f32 v[26:27], v[30:31], v[152:153]
	v_pk_fma_f32 v[24:25], v[28:29], v[134:135], v[24:25]
	v_pk_fma_f32 v[26:27], v[28:29], v[150:151], v[26:27]
	ds_read_b128 v[110:113], v94 offset:12240
	v_add_f32_e32 v34, v24, v25
	v_add_f32_e32 v35, v26, v27
	ds_read_b128 v[126:129], v94 offset:13264
	v_add_f32_dpp v34, v34, v34 quad_perm:[1,0,3,2] row_mask:0xf bank_mask:0xf bound_ctrl:1
	v_add_f32_dpp v35, v35, v35 quad_perm:[1,0,3,2] row_mask:0xf bank_mask:0xf bound_ctrl:1
	ds_read_b128 v[114:117], v94 offset:12496
	v_add_f32_dpp v34, v34, v34 quad_perm:[2,3,0,1] row_mask:0xf bank_mask:0xf bound_ctrl:1
	v_add_f32_dpp v35, v35, v35 quad_perm:[2,3,0,1] row_mask:0xf bank_mask:0xf bound_ctrl:1
	ds_read_b128 v[118:121], v94 offset:12752
	v_add_f32_dpp v34, v34, v34 row_ror:4 row_mask:0xf bank_mask:0xf bound_ctrl:1
	v_add_f32_dpp v35, v35, v35 row_ror:4 row_mask:0xf bank_mask:0xf bound_ctrl:1
	ds_read_b128 v[122:125], v94 offset:13008
	v_add_f32_dpp v34, v34, v34 row_ror:8 row_mask:0xf bank_mask:0xf bound_ctrl:1
	v_add_f32_dpp v35, v35, v35 row_ror:8 row_mask:0xf bank_mask:0xf bound_ctrl:1
	v_pk_mul_f32 v[36:37], v[138:139], v[34:35] op_sel_hi:[1,0]
	v_pk_mul_f32 v[38:39], v[140:141], v[34:35] op_sel_hi:[1,0]
	v_pk_fma_f32 v[36:37], v[146:147], v[154:155], v[36:37] op_sel_hi:[1,0,1] neg_lo:[0,0,1] neg_hi:[0,0,1]
	v_pk_fma_f32 v[38:39], v[148:149], v[154:155], v[38:39] op_sel_hi:[1,0,1] neg_lo:[0,0,1] neg_hi:[0,0,1]
	v_cndmask_b32_e64 v42, v42, v34, s[42:43]
	v_pk_fma_f32 v[28:29], v[28:29], v[142:143], v[36:37]
	v_pk_fma_f32 v[30:31], v[30:31], v[144:145], v[38:39]
	v_cndmask_b32_e64 v43, v43, v35, s[42:43]
	ds_read_b32 v130, v95 offset:13520
	s_waitcnt lgkmcnt(6)
	v_pk_mul_f32 v[24:25], v[30:31], v[52:53]
	v_pk_mul_f32 v[26:27], v[30:31], v[100:101]
	v_pk_fma_f32 v[24:25], v[28:29], v[50:51], v[24:25]
	v_pk_fma_f32 v[26:27], v[28:29], v[98:99], v[26:27]
	ds_read_b128 v[134:137], v94 offset:13600
	v_add_f32_e32 v34, v24, v25
	v_add_f32_e32 v35, v26, v27
	ds_read_b128 v[150:153], v94 offset:14624
	v_add_f32_dpp v34, v34, v34 quad_perm:[1,0,3,2] row_mask:0xf bank_mask:0xf bound_ctrl:1
	v_add_f32_dpp v35, v35, v35 quad_perm:[1,0,3,2] row_mask:0xf bank_mask:0xf bound_ctrl:1
	ds_read_b128 v[138:141], v94 offset:13856
	v_add_f32_dpp v34, v34, v34 quad_perm:[2,3,0,1] row_mask:0xf bank_mask:0xf bound_ctrl:1
	v_add_f32_dpp v35, v35, v35 quad_perm:[2,3,0,1] row_mask:0xf bank_mask:0xf bound_ctrl:1
	ds_read_b128 v[142:145], v94 offset:14112
	v_add_f32_dpp v34, v34, v34 row_ror:4 row_mask:0xf bank_mask:0xf bound_ctrl:1
	v_add_f32_dpp v35, v35, v35 row_ror:4 row_mask:0xf bank_mask:0xf bound_ctrl:1
	ds_read_b128 v[146:149], v94 offset:14368
	v_add_f32_dpp v34, v34, v34 row_ror:8 row_mask:0xf bank_mask:0xf bound_ctrl:1
	v_add_f32_dpp v35, v35, v35 row_ror:8 row_mask:0xf bank_mask:0xf bound_ctrl:1
	v_pk_mul_f32 v[36:37], v[54:55], v[34:35] op_sel_hi:[1,0]
	v_pk_mul_f32 v[38:39], v[56:57], v[34:35] op_sel_hi:[1,0]
	v_pk_fma_f32 v[36:37], v[62:63], v[66:67], v[36:37] op_sel_hi:[1,0,1] neg_lo:[0,0,1] neg_hi:[0,0,1]
	v_pk_fma_f32 v[38:39], v[64:65], v[66:67], v[38:39] op_sel_hi:[1,0,1] neg_lo:[0,0,1] neg_hi:[0,0,1]
	v_cndmask_b32_e64 v42, v42, v34, s[44:45]
	v_pk_fma_f32 v[28:29], v[28:29], v[58:59], v[36:37]
	v_pk_fma_f32 v[30:31], v[30:31], v[60:61], v[38:39]
	v_cndmask_b32_e64 v43, v43, v35, s[44:45]
	ds_read_b32 v154, v95 offset:14880
	s_waitcnt lgkmcnt(6)
	v_pk_mul_f32 v[24:25], v[30:31], v[112:113]
	v_pk_mul_f32 v[26:27], v[30:31], v[128:129]
	v_pk_fma_f32 v[24:25], v[28:29], v[110:111], v[24:25]
	v_pk_fma_f32 v[26:27], v[28:29], v[126:127], v[26:27]
	ds_read_b128 v[50:53], v94 offset:14960
	v_add_f32_e32 v34, v24, v25
	v_add_f32_e32 v35, v26, v27
	ds_read_b128 v[98:101], v94 offset:15984
	v_add_f32_dpp v34, v34, v34 quad_perm:[1,0,3,2] row_mask:0xf bank_mask:0xf bound_ctrl:1
	v_add_f32_dpp v35, v35, v35 quad_perm:[1,0,3,2] row_mask:0xf bank_mask:0xf bound_ctrl:1
	ds_read_b128 v[54:57], v94 offset:15216
	v_add_f32_dpp v34, v34, v34 quad_perm:[2,3,0,1] row_mask:0xf bank_mask:0xf bound_ctrl:1
	v_add_f32_dpp v35, v35, v35 quad_perm:[2,3,0,1] row_mask:0xf bank_mask:0xf bound_ctrl:1
	ds_read_b128 v[58:61], v94 offset:15472
	v_add_f32_dpp v34, v34, v34 row_ror:4 row_mask:0xf bank_mask:0xf bound_ctrl:1
	v_add_f32_dpp v35, v35, v35 row_ror:4 row_mask:0xf bank_mask:0xf bound_ctrl:1
	ds_read_b128 v[62:65], v94 offset:15728
	v_add_f32_dpp v34, v34, v34 row_ror:8 row_mask:0xf bank_mask:0xf bound_ctrl:1
	v_add_f32_dpp v35, v35, v35 row_ror:8 row_mask:0xf bank_mask:0xf bound_ctrl:1
	v_pk_mul_f32 v[36:37], v[114:115], v[34:35] op_sel_hi:[1,0]
	v_pk_mul_f32 v[38:39], v[116:117], v[34:35] op_sel_hi:[1,0]
	v_pk_fma_f32 v[36:37], v[122:123], v[130:131], v[36:37] op_sel_hi:[1,0,1] neg_lo:[0,0,1] neg_hi:[0,0,1]
	v_pk_fma_f32 v[38:39], v[124:125], v[130:131], v[38:39] op_sel_hi:[1,0,1] neg_lo:[0,0,1] neg_hi:[0,0,1]
	v_cndmask_b32_e32 v42, v42, v34, vcc
	v_pk_fma_f32 v[28:29], v[28:29], v[118:119], v[36:37]
	v_pk_fma_f32 v[30:31], v[30:31], v[120:121], v[38:39]
	v_cndmask_b32_e32 v43, v43, v35, vcc
	ds_read_b32 v66, v95 offset:16240
	s_waitcnt lgkmcnt(6)
	v_pk_mul_f32 v[24:25], v[30:31], v[136:137]
	v_pk_mul_f32 v[26:27], v[30:31], v[152:153]
	v_pk_fma_f32 v[24:25], v[28:29], v[134:135], v[24:25]
	v_pk_fma_f32 v[26:27], v[28:29], v[150:151], v[26:27]
	ds_read_b128 v[110:113], v94 offset:16320
	v_add_f32_e32 v34, v24, v25
	v_add_f32_e32 v35, v26, v27
	ds_read_b128 v[126:129], v94 offset:17344
	v_add_f32_dpp v34, v34, v34 quad_perm:[1,0,3,2] row_mask:0xf bank_mask:0xf bound_ctrl:1
	v_add_f32_dpp v35, v35, v35 quad_perm:[1,0,3,2] row_mask:0xf bank_mask:0xf bound_ctrl:1
	ds_read_b128 v[114:117], v94 offset:16576
	v_add_f32_dpp v34, v34, v34 quad_perm:[2,3,0,1] row_mask:0xf bank_mask:0xf bound_ctrl:1
	v_add_f32_dpp v35, v35, v35 quad_perm:[2,3,0,1] row_mask:0xf bank_mask:0xf bound_ctrl:1
	ds_read_b128 v[118:121], v94 offset:16832
	v_add_f32_dpp v34, v34, v34 row_ror:4 row_mask:0xf bank_mask:0xf bound_ctrl:1
	v_add_f32_dpp v35, v35, v35 row_ror:4 row_mask:0xf bank_mask:0xf bound_ctrl:1
	ds_read_b128 v[122:125], v94 offset:17088
	v_add_f32_dpp v34, v34, v34 row_ror:8 row_mask:0xf bank_mask:0xf bound_ctrl:1
	v_add_f32_dpp v35, v35, v35 row_ror:8 row_mask:0xf bank_mask:0xf bound_ctrl:1
	v_pk_mul_f32 v[36:37], v[138:139], v[34:35] op_sel_hi:[1,0]
	v_pk_mul_f32 v[38:39], v[140:141], v[34:35] op_sel_hi:[1,0]
	v_pk_fma_f32 v[36:37], v[146:147], v[154:155], v[36:37] op_sel_hi:[1,0,1] neg_lo:[0,0,1] neg_hi:[0,0,1]
	v_pk_fma_f32 v[38:39], v[148:149], v[154:155], v[38:39] op_sel_hi:[1,0,1] neg_lo:[0,0,1] neg_hi:[0,0,1]
	v_cndmask_b32_e64 v42, v42, v34, s[58:59]
	v_pk_fma_f32 v[28:29], v[28:29], v[142:143], v[36:37]
	v_pk_fma_f32 v[30:31], v[30:31], v[144:145], v[38:39]
	v_cndmask_b32_e64 v43, v43, v35, s[58:59]
	ds_read_b32 v130, v95 offset:17600
	s_waitcnt lgkmcnt(6)
	v_pk_mul_f32 v[24:25], v[30:31], v[52:53]
	v_pk_mul_f32 v[26:27], v[30:31], v[100:101]
	v_pk_fma_f32 v[24:25], v[28:29], v[50:51], v[24:25]
	v_pk_fma_f32 v[26:27], v[28:29], v[98:99], v[26:27]
	ds_read_b128 v[134:137], v94 offset:17680
	v_add_f32_e32 v34, v24, v25
	v_add_f32_e32 v35, v26, v27
	ds_read_b128 v[150:153], v94 offset:18704
	v_add_f32_dpp v34, v34, v34 quad_perm:[1,0,3,2] row_mask:0xf bank_mask:0xf bound_ctrl:1
	v_add_f32_dpp v35, v35, v35 quad_perm:[1,0,3,2] row_mask:0xf bank_mask:0xf bound_ctrl:1
	ds_read_b128 v[138:141], v94 offset:17936
	v_add_f32_dpp v34, v34, v34 quad_perm:[2,3,0,1] row_mask:0xf bank_mask:0xf bound_ctrl:1
	v_add_f32_dpp v35, v35, v35 quad_perm:[2,3,0,1] row_mask:0xf bank_mask:0xf bound_ctrl:1
	ds_read_b128 v[142:145], v94 offset:18192
	v_add_f32_dpp v34, v34, v34 row_ror:4 row_mask:0xf bank_mask:0xf bound_ctrl:1
	v_add_f32_dpp v35, v35, v35 row_ror:4 row_mask:0xf bank_mask:0xf bound_ctrl:1
	ds_read_b128 v[146:149], v94 offset:18448
	v_add_f32_dpp v34, v34, v34 row_ror:8 row_mask:0xf bank_mask:0xf bound_ctrl:1
	v_add_f32_dpp v35, v35, v35 row_ror:8 row_mask:0xf bank_mask:0xf bound_ctrl:1
	v_pk_mul_f32 v[36:37], v[54:55], v[34:35] op_sel_hi:[1,0]
	v_pk_mul_f32 v[38:39], v[56:57], v[34:35] op_sel_hi:[1,0]
	v_pk_fma_f32 v[36:37], v[62:63], v[66:67], v[36:37] op_sel_hi:[1,0,1] neg_lo:[0,0,1] neg_hi:[0,0,1]
	v_pk_fma_f32 v[38:39], v[64:65], v[66:67], v[38:39] op_sel_hi:[1,0,1] neg_lo:[0,0,1] neg_hi:[0,0,1]
	v_cndmask_b32_e64 v42, v42, v34, s[60:61]
	v_pk_fma_f32 v[28:29], v[28:29], v[58:59], v[36:37]
	v_pk_fma_f32 v[30:31], v[30:31], v[60:61], v[38:39]
	v_cndmask_b32_e64 v43, v43, v35, s[60:61]
	ds_read_b32 v154, v95 offset:18960
	s_waitcnt lgkmcnt(6)
	v_pk_mul_f32 v[24:25], v[30:31], v[112:113]
	v_pk_mul_f32 v[26:27], v[30:31], v[128:129]
	v_pk_fma_f32 v[24:25], v[28:29], v[110:111], v[24:25]
	v_pk_fma_f32 v[26:27], v[28:29], v[126:127], v[26:27]
	ds_read_b128 v[50:53], v94 offset:19040
	v_add_f32_e32 v34, v24, v25
	v_add_f32_e32 v35, v26, v27
	ds_read_b128 v[98:101], v94 offset:20064
	v_add_f32_dpp v34, v34, v34 quad_perm:[1,0,3,2] row_mask:0xf bank_mask:0xf bound_ctrl:1
	v_add_f32_dpp v35, v35, v35 quad_perm:[1,0,3,2] row_mask:0xf bank_mask:0xf bound_ctrl:1
	ds_read_b128 v[54:57], v94 offset:19296
	v_add_f32_dpp v34, v34, v34 quad_perm:[2,3,0,1] row_mask:0xf bank_mask:0xf bound_ctrl:1
	v_add_f32_dpp v35, v35, v35 quad_perm:[2,3,0,1] row_mask:0xf bank_mask:0xf bound_ctrl:1
	ds_read_b128 v[58:61], v94 offset:19552
	v_add_f32_dpp v34, v34, v34 row_ror:4 row_mask:0xf bank_mask:0xf bound_ctrl:1
	v_add_f32_dpp v35, v35, v35 row_ror:4 row_mask:0xf bank_mask:0xf bound_ctrl:1
	ds_read_b128 v[62:65], v94 offset:19808
	v_add_f32_dpp v34, v34, v34 row_ror:8 row_mask:0xf bank_mask:0xf bound_ctrl:1
	v_add_f32_dpp v35, v35, v35 row_ror:8 row_mask:0xf bank_mask:0xf bound_ctrl:1
	v_pk_mul_f32 v[36:37], v[114:115], v[34:35] op_sel_hi:[1,0]
	v_pk_mul_f32 v[38:39], v[116:117], v[34:35] op_sel_hi:[1,0]
	v_pk_fma_f32 v[36:37], v[122:123], v[130:131], v[36:37] op_sel_hi:[1,0,1] neg_lo:[0,0,1] neg_hi:[0,0,1]
	v_pk_fma_f32 v[38:39], v[124:125], v[130:131], v[38:39] op_sel_hi:[1,0,1] neg_lo:[0,0,1] neg_hi:[0,0,1]
	v_cndmask_b32_e64 v42, v42, v34, s[62:63]
	v_pk_fma_f32 v[28:29], v[28:29], v[118:119], v[36:37]
	v_pk_fma_f32 v[30:31], v[30:31], v[120:121], v[38:39]
	v_cndmask_b32_e64 v43, v43, v35, s[62:63]
	ds_read_b32 v66, v95 offset:20320
	s_waitcnt lgkmcnt(6)
	v_pk_mul_f32 v[24:25], v[30:31], v[136:137]
	v_pk_mul_f32 v[26:27], v[30:31], v[152:153]
	v_pk_fma_f32 v[24:25], v[28:29], v[134:135], v[24:25]
	v_pk_fma_f32 v[26:27], v[28:29], v[150:151], v[26:27]
	ds_read_b128 v[110:113], v94 offset:20400
	v_add_f32_e32 v34, v24, v25
	v_add_f32_e32 v35, v26, v27
	ds_read_b128 v[126:129], v94 offset:21424
	v_add_f32_dpp v34, v34, v34 quad_perm:[1,0,3,2] row_mask:0xf bank_mask:0xf bound_ctrl:1
	v_add_f32_dpp v35, v35, v35 quad_perm:[1,0,3,2] row_mask:0xf bank_mask:0xf bound_ctrl:1
	ds_read_b128 v[114:117], v94 offset:20656
	v_add_f32_dpp v34, v34, v34 quad_perm:[2,3,0,1] row_mask:0xf bank_mask:0xf bound_ctrl:1
	v_add_f32_dpp v35, v35, v35 quad_perm:[2,3,0,1] row_mask:0xf bank_mask:0xf bound_ctrl:1
	ds_read_b128 v[118:121], v94 offset:20912
	v_add_f32_dpp v34, v34, v34 row_ror:4 row_mask:0xf bank_mask:0xf bound_ctrl:1
	v_add_f32_dpp v35, v35, v35 row_ror:4 row_mask:0xf bank_mask:0xf bound_ctrl:1
	ds_read_b128 v[122:125], v94 offset:21168
	v_add_f32_dpp v34, v34, v34 row_ror:8 row_mask:0xf bank_mask:0xf bound_ctrl:1
	v_add_f32_dpp v35, v35, v35 row_ror:8 row_mask:0xf bank_mask:0xf bound_ctrl:1
	v_pk_mul_f32 v[36:37], v[138:139], v[34:35] op_sel_hi:[1,0]
	v_pk_mul_f32 v[38:39], v[140:141], v[34:35] op_sel_hi:[1,0]
	v_pk_fma_f32 v[36:37], v[146:147], v[154:155], v[36:37] op_sel_hi:[1,0,1] neg_lo:[0,0,1] neg_hi:[0,0,1]
	v_pk_fma_f32 v[38:39], v[148:149], v[154:155], v[38:39] op_sel_hi:[1,0,1] neg_lo:[0,0,1] neg_hi:[0,0,1]
	v_cndmask_b32_e64 v42, v42, v34, s[66:67]
	v_pk_fma_f32 v[28:29], v[28:29], v[142:143], v[36:37]
	v_pk_fma_f32 v[30:31], v[30:31], v[144:145], v[38:39]
	v_cndmask_b32_e64 v43, v43, v35, s[66:67]
	ds_read_b32 v130, v95 offset:21680
	s_waitcnt lgkmcnt(6)
	v_pk_mul_f32 v[24:25], v[30:31], v[52:53]
	v_pk_mul_f32 v[26:27], v[30:31], v[100:101]
	v_pk_fma_f32 v[24:25], v[28:29], v[50:51], v[24:25]
	v_pk_fma_f32 v[26:27], v[28:29], v[98:99], v[26:27]
	v_add_f32_e32 v34, v24, v25
	v_add_f32_e32 v35, v26, v27
	v_lshl_add_u64 v[70:71], v[70:71], 0, s[2:3]
	v_add_f32_dpp v34, v34, v34 quad_perm:[1,0,3,2] row_mask:0xf bank_mask:0xf bound_ctrl:1
	v_add_f32_dpp v35, v35, v35 quad_perm:[1,0,3,2] row_mask:0xf bank_mask:0xf bound_ctrl:1
	v_lshl_add_u64 v[72:73], v[72:73], 0, s[20:21]
	v_add_f32_dpp v34, v34, v34 quad_perm:[2,3,0,1] row_mask:0xf bank_mask:0xf bound_ctrl:1
	v_add_f32_dpp v35, v35, v35 quad_perm:[2,3,0,1] row_mask:0xf bank_mask:0xf bound_ctrl:1
	v_lshl_add_u64 v[74:75], v[74:75], 0, s[20:21]
	v_add_f32_dpp v34, v34, v34 row_ror:4 row_mask:0xf bank_mask:0xf bound_ctrl:1
	v_add_f32_dpp v35, v35, v35 row_ror:4 row_mask:0xf bank_mask:0xf bound_ctrl:1
	s_nop 0
	v_add_f32_dpp v34, v34, v34 row_ror:8 row_mask:0xf bank_mask:0xf bound_ctrl:1
	v_add_f32_dpp v35, v35, v35 row_ror:8 row_mask:0xf bank_mask:0xf bound_ctrl:1
	v_pk_mul_f32 v[36:37], v[54:55], v[34:35] op_sel_hi:[1,0]
	v_pk_mul_f32 v[38:39], v[56:57], v[34:35] op_sel_hi:[1,0]
	v_pk_fma_f32 v[36:37], v[62:63], v[66:67], v[36:37] op_sel_hi:[1,0,1] neg_lo:[0,0,1] neg_hi:[0,0,1]
	v_pk_fma_f32 v[38:39], v[64:65], v[66:67], v[38:39] op_sel_hi:[1,0,1] neg_lo:[0,0,1] neg_hi:[0,0,1]
	v_cndmask_b32_e64 v42, v42, v34, s[64:65]
	v_pk_fma_f32 v[28:29], v[28:29], v[58:59], v[36:37]
	v_pk_fma_f32 v[30:31], v[30:31], v[60:61], v[38:39]
	v_cndmask_b32_e64 v43, v43, v35, s[64:65]
	s_waitcnt lgkmcnt(0)
	v_pk_mul_f32 v[24:25], v[30:31], v[112:113]
	v_pk_mul_f32 v[26:27], v[30:31], v[128:129]
	v_pk_fma_f32 v[24:25], v[28:29], v[110:111], v[24:25]
	v_pk_fma_f32 v[26:27], v[28:29], v[126:127], v[26:27]
	v_add_f32_e32 v34, v24, v25
	v_add_f32_e32 v35, v26, v27
	v_lshl_add_u64 v[32:33], v[68:69], 0, s[0:1]
	v_add_f32_dpp v34, v34, v34 quad_perm:[1,0,3,2] row_mask:0xf bank_mask:0xf bound_ctrl:1
	v_add_f32_dpp v35, v35, v35 quad_perm:[1,0,3,2] row_mask:0xf bank_mask:0xf bound_ctrl:1
	s_nop 0
	v_add_f32_dpp v34, v34, v34 quad_perm:[2,3,0,1] row_mask:0xf bank_mask:0xf bound_ctrl:1
	v_add_f32_dpp v35, v35, v35 quad_perm:[2,3,0,1] row_mask:0xf bank_mask:0xf bound_ctrl:1
	s_nop 0
	v_add_f32_dpp v34, v34, v34 row_ror:4 row_mask:0xf bank_mask:0xf bound_ctrl:1
	v_add_f32_dpp v35, v35, v35 row_ror:4 row_mask:0xf bank_mask:0xf bound_ctrl:1
	s_nop 0
	v_add_f32_dpp v34, v34, v34 row_ror:8 row_mask:0xf bank_mask:0xf bound_ctrl:1
	v_add_f32_dpp v35, v35, v35 row_ror:8 row_mask:0xf bank_mask:0xf bound_ctrl:1
	v_pk_mul_f32 v[36:37], v[114:115], v[34:35] op_sel_hi:[1,0]
	v_pk_mul_f32 v[38:39], v[116:117], v[34:35] op_sel_hi:[1,0]
	v_pk_fma_f32 v[36:37], v[122:123], v[130:131], v[36:37] op_sel_hi:[1,0,1] neg_lo:[0,0,1] neg_hi:[0,0,1]
	v_pk_fma_f32 v[38:39], v[124:125], v[130:131], v[38:39] op_sel_hi:[1,0,1] neg_lo:[0,0,1] neg_hi:[0,0,1]
	v_cndmask_b32_e64 v42, v42, v34, s[68:69]
	v_pk_fma_f32 v[28:29], v[28:29], v[118:119], v[36:37]
	v_pk_fma_f32 v[30:31], v[30:31], v[120:121], v[38:39]
	v_cndmask_b32_e64 v43, v43, v35, s[68:69]
	s_add_u32 s0, s0, 0x1000
	s_addc_u32 s1, s1, 0
	s_add_i32 s24, s24, 1
	v_fma_f32 v40, -v44, v42, v43
	s_cmp_lg_u32 s0, 0xac000
	v_fmac_f32_e32 v40, v48, v45
	global_store_dword v[32:33], v40, off
	s_barrier
	s_cbranch_scc0 .LBB0_81

.LBB0_82:
	v_mov_b32_e32 v236, 0x3e38aa3b
	v_mov_b32_e32 v237, 0x3e38aa3b
	v_and_b32_e32 v230, 63, v157
	v_lshrrev_b32_e32 v231, 6, v157
	v_lshrrev_b32_e32 v232, 3, v230
	v_and_b32_e32 v233, 7, v230
	v_lshrrev_b32_e32 v230, 1, v232
	v_xor_b32_e32 v233, v233, v230
	v_lshlrev_b32_e32 v234, 4, v233
	v_xor_b32_e32 v233, 4, v233
	v_lshlrev_b32_e32 v235, 4, v233
	v_lshl_add_u32 v230, v231, 4, v232
	v_mul_u32_u24_e32 v226, 0x1d00, v230
	v_add_u32_e32 v226, v226, v234
	v_add_u32_e32 v230, 8, v230
	v_mul_u32_u24_e32 v227, 0x1d00, v230
	v_add_u32_e32 v227, v227, v235
	v_lshl_add_u32 v230, v231, 5, v232
	v_lshl_add_u32 v228, v230, 13, v234
	v_add_u32_e32 v230, 8, v230
	v_lshl_add_u32 v229, v230, 13, v235
	v_lshlrev_b32_e32 v230, 11, v231
	v_lshlrev_b32_e32 v231, 12, v231
	s_nop 0
	v_readfirstlane_b32 s76, v230
	v_readfirstlane_b32 s77, v231
	s_nop 0
	s_add_u32 s77, s77, 0x4000
	v_readlane_b32 s0, v253, 41
	v_readlane_b32 s2, v255, 16
	s_add_i32 s0, s2, s0
	s_and_b32 s2, s2, 3
	v_readlane_b32 s4, v253, 7
	s_lshl_b32 s1, s2, 10
	v_readlane_b32 s16, v253, 19
	v_and_b32_e32 v0, 63, v157
	v_readlane_b32 s17, v253, 20
	s_add_u32 s20, s16, s1
	s_addc_u32 s21, s17, 0
	v_lshlrev_b32_e32 v0, 2, v0
	global_load_dword v1, v0, s[20:21]
	global_load_dword v2, v0, s[20:21] offset:256
	v_readlane_b32 s3, v255, 17
	v_readlane_b32 s18, v253, 21
	v_readlane_b32 s19, v253, 22
	v_readlane_b32 s5, v253, 8
	v_readlane_b32 s6, v253, 9
	v_readlane_b32 s7, v253, 10
	v_readlane_b32 s8, v253, 11
	v_readlane_b32 s9, v253, 12
	v_readlane_b32 s10, v253, 13
	v_readlane_b32 s11, v253, 14
	v_readlane_b32 s12, v253, 15
	v_readlane_b32 s13, v253, 16
	v_readlane_b32 s14, v253, 17
	v_readlane_b32 s15, v253, 18
	s_waitcnt vmcnt(0)
	v_mul_f32_e32 v4, v1, v2
	s_nop 1
	v_mov_b32_dpp v4, v4 quad_perm:[1,0,3,2] row_mask:0xf bank_mask:0xf bound_ctrl:1
	v_fmac_f32_e32 v4, v1, v2
	v_mov_b32_e32 v2, v3
	s_nop 0
	v_add_f32_dpp v1, v4, v4 quad_perm:[2,3,0,1] row_mask:0xf bank_mask:0xf bound_ctrl:1
	s_nop 1
	v_add_f32_dpp v1, v1, v1 row_ror:4 row_mask:0xf bank_mask:0xf bound_ctrl:1
	s_nop 1
	v_add_f32_dpp v1, v1, v1 row_ror:8 row_mask:0xf bank_mask:0xf bound_ctrl:1
	s_nop 1
	v_mov_b32_dpp v2, v1 row_bcast:15 row_mask:0xa bank_mask:0xf bound_ctrl:1
	v_add_f32_e32 v1, v1, v2
	v_mov_b32_e32 v2, v3
	s_nop 1
	v_mov_b32_dpp v2, v1 row_bcast:31 row_mask:0xc bank_mask:0xf bound_ctrl:1
	v_add_f32_e32 v1, v1, v2
	s_nop 0
	v_readlane_b32 s1, v1, 63
	global_load_dword v1, v0, s[20:21] offset:512
	s_nop 0
	global_load_dword v0, v0, s[20:21] offset:768
	s_mov_b32 s20, 0x3fb8aa3b
	s_waitcnt vmcnt(0)
	v_mul_f32_e32 v2, v1, v0
	s_nop 1
	v_mov_b32_dpp v2, v2 quad_perm:[1,0,3,2] row_mask:0xf bank_mask:0xf bound_ctrl:1
	v_fmac_f32_e32 v2, v1, v0
	v_mov_b32_e32 v1, v3
	s_nop 0
	v_add_f32_dpp v0, v2, v2 quad_perm:[2,3,0,1] row_mask:0xf bank_mask:0xf bound_ctrl:1
	s_nop 1
	v_add_f32_dpp v0, v0, v0 row_ror:4 row_mask:0xf bank_mask:0xf bound_ctrl:1
	s_nop 1
	v_add_f32_dpp v0, v0, v0 row_ror:8 row_mask:0xf bank_mask:0xf bound_ctrl:1
	s_nop 1
	v_mov_b32_dpp v1, v0 row_bcast:15 row_mask:0xa bank_mask:0xf bound_ctrl:1
	v_add_f32_e32 v0, v0, v1
	v_mov_b32_e32 v1, v3
	s_nop 1
	v_mov_b32_dpp v1, v0 row_bcast:31 row_mask:0xc bank_mask:0xf bound_ctrl:1
	v_add_f32_e32 v0, v0, v1
	s_nop 0
	v_readlane_b32 s3, v0, 63
	v_cvt_f32_ubyte0_e32 v0, s2
	v_mul_f32_e32 v0, 0xbe99999a, v0
	v_mul_f32_e32 v1, 0x3fb8aa3b, v0
	v_fma_f32 v2, v0, s20, -v1
	v_rndne_f32_e32 v4, v1
	v_fmac_f32_e32 v2, 0x32a5705f, v0
	v_sub_f32_e32 v1, v1, v4
	v_add_f32_e32 v1, v1, v2
	v_exp_f32_e32 v1, v1
	v_cvt_i32_f32_e32 v2, v4
	s_mov_b32 s20, 0xc2ce8ed0
	v_cmp_ngt_f32_e32 vcc, s20, v0
	s_mov_b32 s20, 0x42b17218
	v_ldexp_f32 v1, v1, v2
	v_cndmask_b32_e32 v1, 0, v1, vcc
	v_cmp_nlt_f32_e32 vcc, s20, v0
	s_nop 1
	v_cndmask_b32_e32 v0, v190, v1, vcc
	v_mov_b32_e32 v1, 0x3f4ccccd
	v_fmamk_f32 v0, v0, 0xbf19999a, v1
	v_mul_f32_e32 v1, s1, v191
	v_fma_f32 v2, s1, v191, -v1
	v_rndne_f32_e32 v4, v1
	v_fmac_f32_e32 v2, s1, v252
	v_sub_f32_e32 v1, v1, v4
	v_add_f32_e32 v1, v1, v2
	v_exp_f32_e32 v1, v1
	v_cvt_i32_f32_e32 v2, v4
	v_cmp_nlt_f32_e32 vcc, s1, v199
	v_sub_f32_e32 v161, 1.0, v0
	v_ldexp_f32 v1, v1, v2
	v_mul_f32_e32 v2, s3, v191
	v_fma_f32 v4, s3, v191, -v2
	v_rndne_f32_e32 v5, v2
	v_fmac_f32_e32 v4, s3, v252
	v_sub_f32_e32 v2, v2, v5
	v_add_f32_e32 v2, v2, v4
	v_exp_f32_e32 v2, v2
	v_cvt_i32_f32_e32 v4, v5
	v_cndmask_b32_e32 v1, 0, v1, vcc
	v_cmp_ngt_f32_e32 vcc, s1, v194
	s_ashr_i32 s1, s0, 31
	v_ldexp_f32 v2, v2, v4
	v_cndmask_b32_e32 v1, v190, v1, vcc
	v_cmp_nlt_f32_e32 vcc, s3, v199
	s_lshl_b64 s[0:1], s[0:1], 2
	s_add_u32 s0, s96, s0
	v_cndmask_b32_e32 v2, 0, v2, vcc
	v_cmp_ngt_f32_e32 vcc, s3, v194
	s_addc_u32 s1, s97, s1
	s_lshl_b32 s2, s2, 9
	v_cndmask_b32_e32 v2, v190, v2, vcc
	v_sub_f32_e32 v1, v1, v2
	s_add_u32 s38, s18, s2
	v_add_f32_e32 v159, v0, v1
	s_addc_u32 s39, s19, 0
	v_readlane_b32 s0, v255, 16
	s_and_b32 s0, s0, 3
	s_lshl_b32 s0, s0, 9
	s_add_u32 s0, s0, 0x3600
	s_add_u32 s0, s98, s0
	s_addc_u32 s1, s99, 0
	s_branch .LBB0_85

.LBB0_103:
	s_nop 7
	v_max3_f32 v0, v96, s55, v97
	v_max3_f32 v0, v0, v98, v99
	v_max3_f32 v0, v0, v100, v101
	v_max3_f32 v0, v0, v102, v103
	v_max3_f32 v0, v0, v104, v105
	v_max3_f32 v0, v0, v106, v107
	v_max3_f32 v0, v0, v108, v109
	v_max3_f32 v0, v0, v110, v111
	v_max3_f32 v0, v0, v80, v81
	v_max3_f32 v0, v0, v82, v83
	v_max3_f32 v0, v0, v84, v85
	v_max3_f32 v0, v0, v86, v87
	v_and_b32_e32 v4, 64, v198
	v_max3_f32 v0, v0, v88, v89
	v_xor_b32_e32 v1, 32, v198
	v_add_u32_e32 v4, 64, v4
	v_max3_f32 v0, v0, v90, v91
	v_cmp_lt_i32_e32 vcc, v1, v4
	v_max3_f32 v0, v0, v92, v93
	v_max3_f32 v0, v0, v94, v95
	v_cndmask_b32_e32 v1, v198, v1, vcc
	v_lshlrev_b32_e32 v1, 2, v1
	ds_bpermute_b32 v1, v1, v0
	s_waitcnt lgkmcnt(0)
	v_max_f32_e32 v1, v1, v1
	v_max_f32_e32 v0, v0, v1
	v_fmamk_f32 v0, v0, 0x3e38aa3b, v203
	v_max_f32_e32 v1, v216, v216
	v_max_f32_e32 v188, v1, v0
	v_sub_f32_e32 v238, v203, v188
	v_mov_b32_e32 v239, v238
	v_pk_fma_f32 v[240:241], v[96:97], v[236:237], v[238:239]
	v_pk_fma_f32 v[242:243], v[98:99], v[236:237], v[238:239]
	v_exp_f32_e32 v112, v240
	v_exp_f32_e32 v113, v241
	v_pk_fma_f32 v[244:245], v[100:101], v[236:237], v[238:239]
	v_exp_f32_e32 v114, v242
	v_exp_f32_e32 v115, v243
	v_pk_fma_f32 v[246:247], v[102:103], v[236:237], v[238:239]
	v_exp_f32_e32 v116, v244
	v_exp_f32_e32 v117, v245
	v_pk_add_f32 v[248:249], v[112:113], v[114:115]
	v_pk_fma_f32 v[240:241], v[104:105], v[236:237], v[238:239]
	v_exp_f32_e32 v118, v246
	v_exp_f32_e32 v119, v247
	v_pk_add_f32 v[248:249], v[248:249], v[116:117]
	v_pk_fma_f32 v[242:243], v[106:107], v[236:237], v[238:239]
	v_exp_f32_e32 v120, v240
	v_exp_f32_e32 v121, v241
	v_pk_add_f32 v[248:249], v[248:249], v[118:119]
	v_pk_fma_f32 v[244:245], v[108:109], v[236:237], v[238:239]
	v_exp_f32_e32 v122, v242
	v_exp_f32_e32 v123, v243
	v_pk_add_f32 v[248:249], v[248:249], v[120:121]
	v_pk_fma_f32 v[246:247], v[110:111], v[236:237], v[238:239]
	v_exp_f32_e32 v124, v244
	v_exp_f32_e32 v125, v245
	v_pk_add_f32 v[248:249], v[248:249], v[122:123]
	v_pk_fma_f32 v[240:241], v[80:81], v[236:237], v[238:239]
	v_exp_f32_e32 v126, v246
	v_exp_f32_e32 v127, v247
	v_pk_add_f32 v[248:249], v[248:249], v[124:125]
	v_pk_fma_f32 v[242:243], v[82:83], v[236:237], v[238:239]
	v_exp_f32_e32 v0, v240
	v_exp_f32_e32 v1, v241
	v_pk_add_f32 v[248:249], v[248:249], v[126:127]
	v_pk_fma_f32 v[244:245], v[84:85], v[236:237], v[238:239]
	v_exp_f32_e32 v4, v242
	v_exp_f32_e32 v5, v243
	v_pk_add_f32 v[248:249], v[248:249], v[0:1]
	v_pk_fma_f32 v[246:247], v[86:87], v[236:237], v[238:239]
	v_exp_f32_e32 v6, v244
	v_exp_f32_e32 v7, v245
	v_pk_add_f32 v[248:249], v[248:249], v[4:5]
	v_pk_fma_f32 v[240:241], v[88:89], v[236:237], v[238:239]
	v_exp_f32_e32 v12, v246
	v_exp_f32_e32 v13, v247
	v_pk_add_f32 v[248:249], v[248:249], v[6:7]
	v_pk_fma_f32 v[242:243], v[90:91], v[236:237], v[238:239]
	v_exp_f32_e32 v8, v240
	v_exp_f32_e32 v9, v241
	v_pk_add_f32 v[248:249], v[248:249], v[12:13]
	v_pk_fma_f32 v[244:245], v[92:93], v[236:237], v[238:239]
	v_exp_f32_e32 v10, v242
	v_exp_f32_e32 v11, v243
	v_pk_add_f32 v[248:249], v[248:249], v[8:9]
	v_pk_fma_f32 v[180:181], v[94:95], v[236:237], v[238:239]
	v_exp_f32_e32 v14, v244
	v_exp_f32_e32 v15, v245
	v_pk_add_f32 v[248:249], v[248:249], v[10:11]
	v_exp_f32_e32 v178, v180
	v_pk_add_f32 v[248:249], v[248:249], v[14:15]
	v_add_f32_e32 v248, v248, v249
	v_add_f32_e32 v180, v248, v178
	v_mov_b32_e32 v179, v188
	v_sub_f32_e32 v80, v216, v179
	v_exp_f32_e32 v80, v80
	s_nop 0
	v_cmp_neq_f32_e32 vcc, 1.0, v80
	s_cbranch_vccnz .LBB0_99
	s_branch .LBB0_100

.LBB0_113:
	s_nop 4
	v_max3_f32 v0, v84, s55, v85
	v_max3_f32 v0, v0, v86, v87
	v_max3_f32 v0, v0, v88, v89
	v_max3_f32 v0, v0, v90, v91
	v_max3_f32 v0, v0, v92, v93
	v_max3_f32 v0, v0, v94, v95
	v_max3_f32 v0, v0, v96, v97
	v_max3_f32 v0, v0, v98, v99
	v_max3_f32 v0, v0, v68, v69
	v_max3_f32 v0, v0, v70, v71
	v_max3_f32 v0, v0, v72, v73
	v_max3_f32 v0, v0, v74, v75
	v_max3_f32 v0, v0, v76, v77
	v_max3_f32 v0, v0, v78, v79
	v_max3_f32 v0, v0, v80, v81
	v_max3_f32 v0, v0, v82, v83
	ds_bpermute_b32 v1, v176, v0
	v_max_f32_e32 v100, v169, v169
	s_waitcnt lgkmcnt(0)
	v_max_f32_e32 v1, v1, v1
	v_max_f32_e32 v0, v0, v1
	v_fmamk_f32 v0, v0, 0x3e38aa3b, v203
	v_max_f32_e32 v165, v100, v0
	v_sub_f32_e32 v238, v203, v165
	v_mov_b32_e32 v239, v238
	v_pk_fma_f32 v[240:241], v[84:85], v[236:237], v[238:239]
	v_pk_fma_f32 v[242:243], v[86:87], v[236:237], v[238:239]
	v_exp_f32_e32 v100, v240
	v_exp_f32_e32 v101, v241
	v_pk_fma_f32 v[244:245], v[88:89], v[236:237], v[238:239]
	v_exp_f32_e32 v102, v242
	v_exp_f32_e32 v103, v243
	v_pk_fma_f32 v[246:247], v[90:91], v[236:237], v[238:239]
	v_exp_f32_e32 v104, v244
	v_exp_f32_e32 v105, v245
	v_pk_add_f32 v[248:249], v[100:101], v[102:103]
	v_pk_fma_f32 v[240:241], v[92:93], v[236:237], v[238:239]
	v_exp_f32_e32 v106, v246
	v_exp_f32_e32 v107, v247
	v_pk_add_f32 v[248:249], v[248:249], v[104:105]
	v_pk_fma_f32 v[242:243], v[94:95], v[236:237], v[238:239]
	v_exp_f32_e32 v108, v240
	v_exp_f32_e32 v109, v241
	v_pk_add_f32 v[248:249], v[248:249], v[106:107]
	v_pk_fma_f32 v[244:245], v[96:97], v[236:237], v[238:239]
	v_exp_f32_e32 v110, v242
	v_exp_f32_e32 v111, v243
	v_pk_add_f32 v[248:249], v[248:249], v[108:109]
	v_pk_fma_f32 v[246:247], v[98:99], v[236:237], v[238:239]
	v_exp_f32_e32 v112, v244
	v_exp_f32_e32 v113, v245
	v_pk_add_f32 v[248:249], v[248:249], v[110:111]
	v_pk_fma_f32 v[240:241], v[68:69], v[236:237], v[238:239]
	v_exp_f32_e32 v114, v246
	v_exp_f32_e32 v115, v247
	v_pk_add_f32 v[248:249], v[248:249], v[112:113]
	v_pk_fma_f32 v[242:243], v[70:71], v[236:237], v[238:239]
	v_exp_f32_e32 v0, v240
	v_exp_f32_e32 v1, v241
	v_pk_add_f32 v[248:249], v[248:249], v[114:115]
	v_pk_fma_f32 v[244:245], v[72:73], v[236:237], v[238:239]
	v_exp_f32_e32 v118, v242
	v_exp_f32_e32 v119, v243
	v_pk_add_f32 v[248:249], v[248:249], v[0:1]
	v_pk_fma_f32 v[246:247], v[74:75], v[236:237], v[238:239]
	v_exp_f32_e32 v122, v244
	v_exp_f32_e32 v123, v245
	v_pk_add_f32 v[248:249], v[248:249], v[118:119]
	v_pk_fma_f32 v[240:241], v[76:77], v[236:237], v[238:239]
	v_exp_f32_e32 v124, v246
	v_exp_f32_e32 v125, v247
	v_pk_add_f32 v[248:249], v[248:249], v[122:123]
	v_pk_fma_f32 v[242:243], v[78:79], v[236:237], v[238:239]
	v_exp_f32_e32 v116, v240
	v_exp_f32_e32 v117, v241
	v_pk_add_f32 v[248:249], v[248:249], v[124:125]
	v_pk_fma_f32 v[244:245], v[80:81], v[236:237], v[238:239]
	v_exp_f32_e32 v120, v242
	v_exp_f32_e32 v121, v243
	v_pk_add_f32 v[248:249], v[248:249], v[116:117]
	v_pk_fma_f32 v[166:167], v[82:83], v[236:237], v[238:239]
	v_exp_f32_e32 v126, v244
	v_exp_f32_e32 v127, v245
	v_pk_add_f32 v[248:249], v[248:249], v[120:121]
	v_exp_f32_e32 v162, v166
	v_pk_add_f32 v[248:249], v[248:249], v[126:127]
	v_add_f32_e32 v248, v248, v249
	v_add_f32_e32 v166, v248, v162
	v_mov_b32_e32 v163, v165
	v_sub_f32_e32 v68, v169, v163
	v_exp_f32_e32 v68, v68
	s_nop 0
	v_cmp_neq_f32_e32 vcc, 1.0, v68
	s_cbranch_vccnz .LBB0_109
	s_branch .LBB0_110

.LBB0_151:
	s_bitcmp1_b32 s24, 0
	s_cselect_b32 s2, 0x5500, 0
	v_lshl_or_b32 v94, v93, 2, s2
	v_lshl_add_u32 v95, v0, 2, s2
	v_mov_b32_e32 v96, s2
	v_mul_u32_u24_e32 v46, 0x154, v93
	v_add_u32_e32 v47, v46, v96
	v_add_u32_e32 v46, v46, v95
	ds_read_b64 v[44:45], v47 offset:1344
	ds_read_b32 v48, v46 offset:1280
	ds_read_b128 v[110:113], v94
	ds_read_b128 v[126:129], v94 offset:1024
	ds_read_b128 v[114:117], v94 offset:256
	ds_read_b128 v[118:121], v94 offset:512
	ds_read_b128 v[122:125], v94 offset:768
	ds_read_b32 v130, v95 offset:1280
	ds_read_b128 v[134:137], v94 offset:1360
	ds_read_b128 v[150:153], v94 offset:2384
	ds_read_b128 v[138:141], v94 offset:1616
	ds_read_b128 v[142:145], v94 offset:1872
	ds_read_b128 v[146:149], v94 offset:2128
	ds_read_b32 v154, v95 offset:2640
	s_mov_b64 s[2:3], 0x100
	s_mov_b64 s[20:21], 0x800
	s_waitcnt lgkmcnt(6)
	v_pk_mul_f32 v[24:25], v[30:31], v[112:113]
	v_pk_mul_f32 v[26:27], v[30:31], v[128:129]
	v_pk_fma_f32 v[24:25], v[28:29], v[110:111], v[24:25]
	v_pk_fma_f32 v[26:27], v[28:29], v[126:127], v[26:27]
	ds_read_b128 v[50:53], v94 offset:2720
	v_add_f32_e32 v34, v24, v25
	v_add_f32_e32 v35, v26, v27
	ds_read_b128 v[98:101], v94 offset:3744
	v_add_f32_dpp v34, v34, v34 quad_perm:[1,0,3,2] row_mask:0xf bank_mask:0xf bound_ctrl:1
	v_add_f32_dpp v35, v35, v35 quad_perm:[1,0,3,2] row_mask:0xf bank_mask:0xf bound_ctrl:1
	ds_read_b128 v[54:57], v94 offset:2976
	v_add_f32_dpp v34, v34, v34 quad_perm:[2,3,0,1] row_mask:0xf bank_mask:0xf bound_ctrl:1
	v_add_f32_dpp v35, v35, v35 quad_perm:[2,3,0,1] row_mask:0xf bank_mask:0xf bound_ctrl:1
	ds_read_b128 v[58:61], v94 offset:3232
	v_add_f32_dpp v34, v34, v34 row_ror:4 row_mask:0xf bank_mask:0xf bound_ctrl:1
	v_add_f32_dpp v35, v35, v35 row_ror:4 row_mask:0xf bank_mask:0xf bound_ctrl:1
	ds_read_b128 v[62:65], v94 offset:3488
	v_add_f32_dpp v34, v34, v34 row_ror:8 row_mask:0xf bank_mask:0xf bound_ctrl:1
	v_add_f32_dpp v35, v35, v35 row_ror:8 row_mask:0xf bank_mask:0xf bound_ctrl:1
	v_pk_mul_f32 v[36:37], v[114:115], v[34:35] op_sel_hi:[1,0]
	v_pk_mul_f32 v[38:39], v[116:117], v[34:35] op_sel_hi:[1,0]
	v_pk_fma_f32 v[36:37], v[122:123], v[130:131], v[36:37] op_sel_hi:[1,0,1] neg_lo:[0,0,1] neg_hi:[0,0,1]
	v_pk_fma_f32 v[38:39], v[124:125], v[130:131], v[38:39] op_sel_hi:[1,0,1] neg_lo:[0,0,1] neg_hi:[0,0,1]
	v_cndmask_b32_e64 v42, 0, v34, s[72:73]
	v_pk_fma_f32 v[28:29], v[28:29], v[118:119], v[36:37]
	v_pk_fma_f32 v[30:31], v[30:31], v[120:121], v[38:39]
	v_cndmask_b32_e64 v43, 0, v35, s[72:73]
	ds_read_b32 v66, v95 offset:4000
	s_waitcnt lgkmcnt(6)
	v_pk_mul_f32 v[24:25], v[30:31], v[136:137]
	v_pk_mul_f32 v[26:27], v[30:31], v[152:153]
	v_pk_fma_f32 v[24:25], v[28:29], v[134:135], v[24:25]
	v_pk_fma_f32 v[26:27], v[28:29], v[150:151], v[26:27]
	ds_read_b128 v[110:113], v94 offset:4080
	v_add_f32_e32 v34, v24, v25
	v_add_f32_e32 v35, v26, v27
	ds_read_b128 v[126:129], v94 offset:5104
	v_add_f32_dpp v34, v34, v34 quad_perm:[1,0,3,2] row_mask:0xf bank_mask:0xf bound_ctrl:1
	v_add_f32_dpp v35, v35, v35 quad_perm:[1,0,3,2] row_mask:0xf bank_mask:0xf bound_ctrl:1
	ds_read_b128 v[114:117], v94 offset:4336
	v_add_f32_dpp v34, v34, v34 quad_perm:[2,3,0,1] row_mask:0xf bank_mask:0xf bound_ctrl:1
	v_add_f32_dpp v35, v35, v35 quad_perm:[2,3,0,1] row_mask:0xf bank_mask:0xf bound_ctrl:1
	ds_read_b128 v[118:121], v94 offset:4592
	v_add_f32_dpp v34, v34, v34 row_ror:4 row_mask:0xf bank_mask:0xf bound_ctrl:1
	v_add_f32_dpp v35, v35, v35 row_ror:4 row_mask:0xf bank_mask:0xf bound_ctrl:1
	ds_read_b128 v[122:125], v94 offset:4848
	v_add_f32_dpp v34, v34, v34 row_ror:8 row_mask:0xf bank_mask:0xf bound_ctrl:1
	v_add_f32_dpp v35, v35, v35 row_ror:8 row_mask:0xf bank_mask:0xf bound_ctrl:1
	v_pk_mul_f32 v[36:37], v[138:139], v[34:35] op_sel_hi:[1,0]
	v_pk_mul_f32 v[38:39], v[140:141], v[34:35] op_sel_hi:[1,0]
	v_pk_fma_f32 v[36:37], v[146:147], v[154:155], v[36:37] op_sel_hi:[1,0,1] neg_lo:[0,0,1] neg_hi:[0,0,1]
	v_pk_fma_f32 v[38:39], v[148:149], v[154:155], v[38:39] op_sel_hi:[1,0,1] neg_lo:[0,0,1] neg_hi:[0,0,1]
	v_cndmask_b32_e64 v42, v42, v34, s[30:31]
	v_pk_fma_f32 v[28:29], v[28:29], v[142:143], v[36:37]
	v_pk_fma_f32 v[30:31], v[30:31], v[144:145], v[38:39]
	v_cndmask_b32_e64 v43, v43, v35, s[30:31]
	ds_read_b32 v130, v95 offset:5360
	s_waitcnt lgkmcnt(6)
	v_pk_mul_f32 v[24:25], v[30:31], v[52:53]
	v_pk_mul_f32 v[26:27], v[30:31], v[100:101]
	v_pk_fma_f32 v[24:25], v[28:29], v[50:51], v[24:25]
	v_pk_fma_f32 v[26:27], v[28:29], v[98:99], v[26:27]
	ds_read_b128 v[134:137], v94 offset:5440
	v_add_f32_e32 v34, v24, v25
	v_add_f32_e32 v35, v26, v27
	ds_read_b128 v[150:153], v94 offset:6464
	v_add_f32_dpp v34, v34, v34 quad_perm:[1,0,3,2] row_mask:0xf bank_mask:0xf bound_ctrl:1
	v_add_f32_dpp v35, v35, v35 quad_perm:[1,0,3,2] row_mask:0xf bank_mask:0xf bound_ctrl:1
	ds_read_b128 v[138:141], v94 offset:5696
	v_add_f32_dpp v34, v34, v34 quad_perm:[2,3,0,1] row_mask:0xf bank_mask:0xf bound_ctrl:1
	v_add_f32_dpp v35, v35, v35 quad_perm:[2,3,0,1] row_mask:0xf bank_mask:0xf bound_ctrl:1
	ds_read_b128 v[142:145], v94 offset:5952
	v_add_f32_dpp v34, v34, v34 row_ror:4 row_mask:0xf bank_mask:0xf bound_ctrl:1
	v_add_f32_dpp v35, v35, v35 row_ror:4 row_mask:0xf bank_mask:0xf bound_ctrl:1
	ds_read_b128 v[146:149], v94 offset:6208
	v_add_f32_dpp v34, v34, v34 row_ror:8 row_mask:0xf bank_mask:0xf bound_ctrl:1
	v_add_f32_dpp v35, v35, v35 row_ror:8 row_mask:0xf bank_mask:0xf bound_ctrl:1
	v_pk_mul_f32 v[36:37], v[54:55], v[34:35] op_sel_hi:[1,0]
	v_pk_mul_f32 v[38:39], v[56:57], v[34:35] op_sel_hi:[1,0]
	v_pk_fma_f32 v[36:37], v[62:63], v[66:67], v[36:37] op_sel_hi:[1,0,1] neg_lo:[0,0,1] neg_hi:[0,0,1]
	v_pk_fma_f32 v[38:39], v[64:65], v[66:67], v[38:39] op_sel_hi:[1,0,1] neg_lo:[0,0,1] neg_hi:[0,0,1]
	v_cndmask_b32_e64 v42, v42, v34, s[70:71]
	v_pk_fma_f32 v[28:29], v[28:29], v[58:59], v[36:37]
	v_pk_fma_f32 v[30:31], v[30:31], v[60:61], v[38:39]
	v_cndmask_b32_e64 v43, v43, v35, s[70:71]
	ds_read_b32 v154, v95 offset:6720
	s_waitcnt lgkmcnt(6)
	v_pk_mul_f32 v[24:25], v[30:31], v[112:113]
	v_pk_mul_f32 v[26:27], v[30:31], v[128:129]
	v_pk_fma_f32 v[24:25], v[28:29], v[110:111], v[24:25]
	v_pk_fma_f32 v[26:27], v[28:29], v[126:127], v[26:27]
	ds_read_b128 v[50:53], v94 offset:6800
	v_add_f32_e32 v34, v24, v25
	v_add_f32_e32 v35, v26, v27
	ds_read_b128 v[98:101], v94 offset:7824
	v_add_f32_dpp v34, v34, v34 quad_perm:[1,0,3,2] row_mask:0xf bank_mask:0xf bound_ctrl:1
	v_add_f32_dpp v35, v35, v35 quad_perm:[1,0,3,2] row_mask:0xf bank_mask:0xf bound_ctrl:1
	ds_read_b128 v[54:57], v94 offset:7056
	v_add_f32_dpp v34, v34, v34 quad_perm:[2,3,0,1] row_mask:0xf bank_mask:0xf bound_ctrl:1
	v_add_f32_dpp v35, v35, v35 quad_perm:[2,3,0,1] row_mask:0xf bank_mask:0xf bound_ctrl:1
	ds_read_b128 v[58:61], v94 offset:7312
	v_add_f32_dpp v34, v34, v34 row_ror:4 row_mask:0xf bank_mask:0xf bound_ctrl:1
	v_add_f32_dpp v35, v35, v35 row_ror:4 row_mask:0xf bank_mask:0xf bound_ctrl:1
	ds_read_b128 v[62:65], v94 offset:7568
	v_add_f32_dpp v34, v34, v34 row_ror:8 row_mask:0xf bank_mask:0xf bound_ctrl:1
	v_add_f32_dpp v35, v35, v35 row_ror:8 row_mask:0xf bank_mask:0xf bound_ctrl:1
	v_pk_mul_f32 v[36:37], v[114:115], v[34:35] op_sel_hi:[1,0]
	v_pk_mul_f32 v[38:39], v[116:117], v[34:35] op_sel_hi:[1,0]
	v_pk_fma_f32 v[36:37], v[122:123], v[130:131], v[36:37] op_sel_hi:[1,0,1] neg_lo:[0,0,1] neg_hi:[0,0,1]
	v_pk_fma_f32 v[38:39], v[124:125], v[130:131], v[38:39] op_sel_hi:[1,0,1] neg_lo:[0,0,1] neg_hi:[0,0,1]
	v_cndmask_b32_e64 v42, v42, v34, s[40:41]
	v_pk_fma_f32 v[28:29], v[28:29], v[118:119], v[36:37]
	v_pk_fma_f32 v[30:31], v[30:31], v[120:121], v[38:39]
	v_cndmask_b32_e64 v43, v43, v35, s[40:41]
	ds_read_b32 v66, v95 offset:8080
	s_waitcnt lgkmcnt(6)
	v_pk_mul_f32 v[24:25], v[30:31], v[136:137]
	v_pk_mul_f32 v[26:27], v[30:31], v[152:153]
	v_pk_fma_f32 v[24:25], v[28:29], v[134:135], v[24:25]
	v_pk_fma_f32 v[26:27], v[28:29], v[150:151], v[26:27]
	ds_read_b128 v[110:113], v94 offset:8160
	v_add_f32_e32 v34, v24, v25
	v_add_f32_e32 v35, v26, v27
	ds_read_b128 v[126:129], v94 offset:9184
	v_add_f32_dpp v34, v34, v34 quad_perm:[1,0,3,2] row_mask:0xf bank_mask:0xf bound_ctrl:1
	v_add_f32_dpp v35, v35, v35 quad_perm:[1,0,3,2] row_mask:0xf bank_mask:0xf bound_ctrl:1
	ds_read_b128 v[114:117], v94 offset:8416
	v_add_f32_dpp v34, v34, v34 quad_perm:[2,3,0,1] row_mask:0xf bank_mask:0xf bound_ctrl:1
	v_add_f32_dpp v35, v35, v35 quad_perm:[2,3,0,1] row_mask:0xf bank_mask:0xf bound_ctrl:1
	ds_read_b128 v[118:121], v94 offset:8672
	v_add_f32_dpp v34, v34, v34 row_ror:4 row_mask:0xf bank_mask:0xf bound_ctrl:1
	v_add_f32_dpp v35, v35, v35 row_ror:4 row_mask:0xf bank_mask:0xf bound_ctrl:1
	ds_read_b128 v[122:125], v94 offset:8928
	v_add_f32_dpp v34, v34, v34 row_ror:8 row_mask:0xf bank_mask:0xf bound_ctrl:1
	v_add_f32_dpp v35, v35, v35 row_ror:8 row_mask:0xf bank_mask:0xf bound_ctrl:1
	v_pk_mul_f32 v[36:37], v[138:139], v[34:35] op_sel_hi:[1,0]
	v_pk_mul_f32 v[38:39], v[140:141], v[34:35] op_sel_hi:[1,0]
	v_pk_fma_f32 v[36:37], v[146:147], v[154:155], v[36:37] op_sel_hi:[1,0,1] neg_lo:[0,0,1] neg_hi:[0,0,1]
	v_pk_fma_f32 v[38:39], v[148:149], v[154:155], v[38:39] op_sel_hi:[1,0,1] neg_lo:[0,0,1] neg_hi:[0,0,1]
	v_cndmask_b32_e64 v42, v42, v34, s[42:43]
	v_pk_fma_f32 v[28:29], v[28:29], v[142:143], v[36:37]
	v_pk_fma_f32 v[30:31], v[30:31], v[144:145], v[38:39]
	v_cndmask_b32_e64 v43, v43, v35, s[42:43]
	ds_read_b32 v130, v95 offset:9440
	s_waitcnt lgkmcnt(6)
	v_pk_mul_f32 v[24:25], v[30:31], v[52:53]
	v_pk_mul_f32 v[26:27], v[30:31], v[100:101]
	v_pk_fma_f32 v[24:25], v[28:29], v[50:51], v[24:25]
	v_pk_fma_f32 v[26:27], v[28:29], v[98:99], v[26:27]
	ds_read_b128 v[134:137], v94 offset:9520
	v_add_f32_e32 v34, v24, v25
	v_add_f32_e32 v35, v26, v27
	ds_read_b128 v[150:153], v94 offset:10544
	v_add_f32_dpp v34, v34, v34 quad_perm:[1,0,3,2] row_mask:0xf bank_mask:0xf bound_ctrl:1
	v_add_f32_dpp v35, v35, v35 quad_perm:[1,0,3,2] row_mask:0xf bank_mask:0xf bound_ctrl:1
	ds_read_b128 v[138:141], v94 offset:9776
	v_add_f32_dpp v34, v34, v34 quad_perm:[2,3,0,1] row_mask:0xf bank_mask:0xf bound_ctrl:1
	v_add_f32_dpp v35, v35, v35 quad_perm:[2,3,0,1] row_mask:0xf bank_mask:0xf bound_ctrl:1
	ds_read_b128 v[142:145], v94 offset:10032
	v_add_f32_dpp v34, v34, v34 row_ror:4 row_mask:0xf bank_mask:0xf bound_ctrl:1
	v_add_f32_dpp v35, v35, v35 row_ror:4 row_mask:0xf bank_mask:0xf bound_ctrl:1
	ds_read_b128 v[146:149], v94 offset:10288
	v_add_f32_dpp v34, v34, v34 row_ror:8 row_mask:0xf bank_mask:0xf bound_ctrl:1
	v_add_f32_dpp v35, v35, v35 row_ror:8 row_mask:0xf bank_mask:0xf bound_ctrl:1
	v_pk_mul_f32 v[36:37], v[54:55], v[34:35] op_sel_hi:[1,0]
	v_pk_mul_f32 v[38:39], v[56:57], v[34:35] op_sel_hi:[1,0]
	v_pk_fma_f32 v[36:37], v[62:63], v[66:67], v[36:37] op_sel_hi:[1,0,1] neg_lo:[0,0,1] neg_hi:[0,0,1]
	v_pk_fma_f32 v[38:39], v[64:65], v[66:67], v[38:39] op_sel_hi:[1,0,1] neg_lo:[0,0,1] neg_hi:[0,0,1]
	v_cndmask_b32_e64 v42, v42, v34, s[44:45]
	v_pk_fma_f32 v[28:29], v[28:29], v[58:59], v[36:37]
	v_pk_fma_f32 v[30:31], v[30:31], v[60:61], v[38:39]
	v_cndmask_b32_e64 v43, v43, v35, s[44:45]
	ds_read_b32 v154, v95 offset:10800
	s_waitcnt lgkmcnt(6)
	v_pk_mul_f32 v[24:25], v[30:31], v[112:113]
	v_pk_mul_f32 v[26:27], v[30:31], v[128:129]
	v_pk_fma_f32 v[24:25], v[28:29], v[110:111], v[24:25]
	v_pk_fma_f32 v[26:27], v[28:29], v[126:127], v[26:27]
	ds_read_b128 v[50:53], v94 offset:10880
	v_add_f32_e32 v34, v24, v25
	v_add_f32_e32 v35, v26, v27
	ds_read_b128 v[98:101], v94 offset:11904
	v_add_f32_dpp v34, v34, v34 quad_perm:[1,0,3,2] row_mask:0xf bank_mask:0xf bound_ctrl:1
	v_add_f32_dpp v35, v35, v35 quad_perm:[1,0,3,2] row_mask:0xf bank_mask:0xf bound_ctrl:1
	ds_read_b128 v[54:57], v94 offset:11136
	v_add_f32_dpp v34, v34, v34 quad_perm:[2,3,0,1] row_mask:0xf bank_mask:0xf bound_ctrl:1
	v_add_f32_dpp v35, v35, v35 quad_perm:[2,3,0,1] row_mask:0xf bank_mask:0xf bound_ctrl:1
	ds_read_b128 v[58:61], v94 offset:11392
	v_add_f32_dpp v34, v34, v34 row_ror:4 row_mask:0xf bank_mask:0xf bound_ctrl:1
	v_add_f32_dpp v35, v35, v35 row_ror:4 row_mask:0xf bank_mask:0xf bound_ctrl:1
	ds_read_b128 v[62:65], v94 offset:11648
	v_add_f32_dpp v34, v34, v34 row_ror:8 row_mask:0xf bank_mask:0xf bound_ctrl:1
	v_add_f32_dpp v35, v35, v35 row_ror:8 row_mask:0xf bank_mask:0xf bound_ctrl:1
	v_pk_mul_f32 v[36:37], v[114:115], v[34:35] op_sel_hi:[1,0]
	v_pk_mul_f32 v[38:39], v[116:117], v[34:35] op_sel_hi:[1,0]
	v_pk_fma_f32 v[36:37], v[122:123], v[130:131], v[36:37] op_sel_hi:[1,0,1] neg_lo:[0,0,1] neg_hi:[0,0,1]
	v_pk_fma_f32 v[38:39], v[124:125], v[130:131], v[38:39] op_sel_hi:[1,0,1] neg_lo:[0,0,1] neg_hi:[0,0,1]
	v_cndmask_b32_e64 v42, v42, v34, s[46:47]
	v_pk_fma_f32 v[28:29], v[28:29], v[118:119], v[36:37]
	v_pk_fma_f32 v[30:31], v[30:31], v[120:121], v[38:39]
	v_cndmask_b32_e64 v43, v43, v35, s[46:47]
	ds_read_b32 v66, v95 offset:12160
	s_waitcnt lgkmcnt(6)
	v_pk_mul_f32 v[24:25], v[30:31], v[136:137]
	v_pk_mul_f32 v[26:27], v[30:31], v[152:153]
	v_pk_fma_f32 v[24:25], v[28:29], v[134:135], v[24:25]
	v_pk_fma_f32 v[26:27], v[28:29], v[150:151], v[26:27]
	ds_read_b128 v[110:113], v94 offset:12240
	v_add_f32_e32 v34, v24, v25
	v_add_f32_e32 v35, v26, v27
	ds_read_b128 v[126:129], v94 offset:13264
	v_add_f32_dpp v34, v34, v34 quad_perm:[1,0,3,2] row_mask:0xf bank_mask:0xf bound_ctrl:1
	v_add_f32_dpp v35, v35, v35 quad_perm:[1,0,3,2] row_mask:0xf bank_mask:0xf bound_ctrl:1
	ds_read_b128 v[114:117], v94 offset:12496
	v_add_f32_dpp v34, v34, v34 quad_perm:[2,3,0,1] row_mask:0xf bank_mask:0xf bound_ctrl:1
	v_add_f32_dpp v35, v35, v35 quad_perm:[2,3,0,1] row_mask:0xf bank_mask:0xf bound_ctrl:1
	ds_read_b128 v[118:121], v94 offset:12752
	v_add_f32_dpp v34, v34, v34 row_ror:4 row_mask:0xf bank_mask:0xf bound_ctrl:1
	v_add_f32_dpp v35, v35, v35 row_ror:4 row_mask:0xf bank_mask:0xf bound_ctrl:1
	ds_read_b128 v[122:125], v94 offset:13008
	v_add_f32_dpp v34, v34, v34 row_ror:8 row_mask:0xf bank_mask:0xf bound_ctrl:1
	v_add_f32_dpp v35, v35, v35 row_ror:8 row_mask:0xf bank_mask:0xf bound_ctrl:1
	v_pk_mul_f32 v[36:37], v[138:139], v[34:35] op_sel_hi:[1,0]
	v_pk_mul_f32 v[38:39], v[140:141], v[34:35] op_sel_hi:[1,0]
	v_pk_fma_f32 v[36:37], v[146:147], v[154:155], v[36:37] op_sel_hi:[1,0,1] neg_lo:[0,0,1] neg_hi:[0,0,1]
	v_pk_fma_f32 v[38:39], v[148:149], v[154:155], v[38:39] op_sel_hi:[1,0,1] neg_lo:[0,0,1] neg_hi:[0,0,1]
	v_cndmask_b32_e64 v42, v42, v34, s[58:59]
	v_pk_fma_f32 v[28:29], v[28:29], v[142:143], v[36:37]
	v_pk_fma_f32 v[30:31], v[30:31], v[144:145], v[38:39]
	v_cndmask_b32_e64 v43, v43, v35, s[58:59]
	ds_read_b32 v130, v95 offset:13520
	s_waitcnt lgkmcnt(6)
	v_pk_mul_f32 v[24:25], v[30:31], v[52:53]
	v_pk_mul_f32 v[26:27], v[30:31], v[100:101]
	v_pk_fma_f32 v[24:25], v[28:29], v[50:51], v[24:25]
	v_pk_fma_f32 v[26:27], v[28:29], v[98:99], v[26:27]
	ds_read_b128 v[134:137], v94 offset:13600
	v_add_f32_e32 v34, v24, v25
	v_add_f32_e32 v35, v26, v27
	ds_read_b128 v[150:153], v94 offset:14624
	v_add_f32_dpp v34, v34, v34 quad_perm:[1,0,3,2] row_mask:0xf bank_mask:0xf bound_ctrl:1
	v_add_f32_dpp v35, v35, v35 quad_perm:[1,0,3,2] row_mask:0xf bank_mask:0xf bound_ctrl:1
	ds_read_b128 v[138:141], v94 offset:13856
	v_add_f32_dpp v34, v34, v34 quad_perm:[2,3,0,1] row_mask:0xf bank_mask:0xf bound_ctrl:1
	v_add_f32_dpp v35, v35, v35 quad_perm:[2,3,0,1] row_mask:0xf bank_mask:0xf bound_ctrl:1
	ds_read_b128 v[142:145], v94 offset:14112
	v_add_f32_dpp v34, v34, v34 row_ror:4 row_mask:0xf bank_mask:0xf bound_ctrl:1
	v_add_f32_dpp v35, v35, v35 row_ror:4 row_mask:0xf bank_mask:0xf bound_ctrl:1
	ds_read_b128 v[146:149], v94 offset:14368
	v_add_f32_dpp v34, v34, v34 row_ror:8 row_mask:0xf bank_mask:0xf bound_ctrl:1
	v_add_f32_dpp v35, v35, v35 row_ror:8 row_mask:0xf bank_mask:0xf bound_ctrl:1
	v_pk_mul_f32 v[36:37], v[54:55], v[34:35] op_sel_hi:[1,0]
	v_pk_mul_f32 v[38:39], v[56:57], v[34:35] op_sel_hi:[1,0]
	v_pk_fma_f32 v[36:37], v[62:63], v[66:67], v[36:37] op_sel_hi:[1,0,1] neg_lo:[0,0,1] neg_hi:[0,0,1]
	v_pk_fma_f32 v[38:39], v[64:65], v[66:67], v[38:39] op_sel_hi:[1,0,1] neg_lo:[0,0,1] neg_hi:[0,0,1]
	v_cndmask_b32_e64 v42, v42, v34, s[60:61]
	v_pk_fma_f32 v[28:29], v[28:29], v[58:59], v[36:37]
	v_pk_fma_f32 v[30:31], v[30:31], v[60:61], v[38:39]
	v_cndmask_b32_e64 v43, v43, v35, s[60:61]
	ds_read_b32 v154, v95 offset:14880
	s_waitcnt lgkmcnt(6)
	v_pk_mul_f32 v[24:25], v[30:31], v[112:113]
	v_pk_mul_f32 v[26:27], v[30:31], v[128:129]
	v_pk_fma_f32 v[24:25], v[28:29], v[110:111], v[24:25]
	v_pk_fma_f32 v[26:27], v[28:29], v[126:127], v[26:27]
	ds_read_b128 v[50:53], v94 offset:14960
	v_add_f32_e32 v34, v24, v25
	v_add_f32_e32 v35, v26, v27
	ds_read_b128 v[98:101], v94 offset:15984
	v_add_f32_dpp v34, v34, v34 quad_perm:[1,0,3,2] row_mask:0xf bank_mask:0xf bound_ctrl:1
	v_add_f32_dpp v35, v35, v35 quad_perm:[1,0,3,2] row_mask:0xf bank_mask:0xf bound_ctrl:1
	ds_read_b128 v[54:57], v94 offset:15216
	v_add_f32_dpp v34, v34, v34 quad_perm:[2,3,0,1] row_mask:0xf bank_mask:0xf bound_ctrl:1
	v_add_f32_dpp v35, v35, v35 quad_perm:[2,3,0,1] row_mask:0xf bank_mask:0xf bound_ctrl:1
	ds_read_b128 v[58:61], v94 offset:15472
	v_add_f32_dpp v34, v34, v34 row_ror:4 row_mask:0xf bank_mask:0xf bound_ctrl:1
	v_add_f32_dpp v35, v35, v35 row_ror:4 row_mask:0xf bank_mask:0xf bound_ctrl:1
	ds_read_b128 v[62:65], v94 offset:15728
	v_add_f32_dpp v34, v34, v34 row_ror:8 row_mask:0xf bank_mask:0xf bound_ctrl:1
	v_add_f32_dpp v35, v35, v35 row_ror:8 row_mask:0xf bank_mask:0xf bound_ctrl:1
	v_pk_mul_f32 v[36:37], v[114:115], v[34:35] op_sel_hi:[1,0]
	v_pk_mul_f32 v[38:39], v[116:117], v[34:35] op_sel_hi:[1,0]
	v_pk_fma_f32 v[36:37], v[122:123], v[130:131], v[36:37] op_sel_hi:[1,0,1] neg_lo:[0,0,1] neg_hi:[0,0,1]
	v_pk_fma_f32 v[38:39], v[124:125], v[130:131], v[38:39] op_sel_hi:[1,0,1] neg_lo:[0,0,1] neg_hi:[0,0,1]
	v_cndmask_b32_e64 v42, v42, v34, s[62:63]
	v_pk_fma_f32 v[28:29], v[28:29], v[118:119], v[36:37]
	v_pk_fma_f32 v[30:31], v[30:31], v[120:121], v[38:39]
	v_cndmask_b32_e64 v43, v43, v35, s[62:63]
	ds_read_b32 v66, v95 offset:16240
	s_waitcnt lgkmcnt(6)
	v_pk_mul_f32 v[24:25], v[30:31], v[136:137]
	v_pk_mul_f32 v[26:27], v[30:31], v[152:153]
	v_pk_fma_f32 v[24:25], v[28:29], v[134:135], v[24:25]
	v_pk_fma_f32 v[26:27], v[28:29], v[150:151], v[26:27]
	ds_read_b128 v[110:113], v94 offset:16320
	v_add_f32_e32 v34, v24, v25
	v_add_f32_e32 v35, v26, v27
	ds_read_b128 v[126:129], v94 offset:17344
	v_add_f32_dpp v34, v34, v34 quad_perm:[1,0,3,2] row_mask:0xf bank_mask:0xf bound_ctrl:1
	v_add_f32_dpp v35, v35, v35 quad_perm:[1,0,3,2] row_mask:0xf bank_mask:0xf bound_ctrl:1
	ds_read_b128 v[114:117], v94 offset:16576
	v_add_f32_dpp v34, v34, v34 quad_perm:[2,3,0,1] row_mask:0xf bank_mask:0xf bound_ctrl:1
	v_add_f32_dpp v35, v35, v35 quad_perm:[2,3,0,1] row_mask:0xf bank_mask:0xf bound_ctrl:1
	ds_read_b128 v[118:121], v94 offset:16832
	v_add_f32_dpp v34, v34, v34 row_ror:4 row_mask:0xf bank_mask:0xf bound_ctrl:1
	v_add_f32_dpp v35, v35, v35 row_ror:4 row_mask:0xf bank_mask:0xf bound_ctrl:1
	ds_read_b128 v[122:125], v94 offset:17088
	v_add_f32_dpp v34, v34, v34 row_ror:8 row_mask:0xf bank_mask:0xf bound_ctrl:1
	v_add_f32_dpp v35, v35, v35 row_ror:8 row_mask:0xf bank_mask:0xf bound_ctrl:1
	v_pk_mul_f32 v[36:37], v[138:139], v[34:35] op_sel_hi:[1,0]
	v_pk_mul_f32 v[38:39], v[140:141], v[34:35] op_sel_hi:[1,0]
	v_pk_fma_f32 v[36:37], v[146:147], v[154:155], v[36:37] op_sel_hi:[1,0,1] neg_lo:[0,0,1] neg_hi:[0,0,1]
	v_pk_fma_f32 v[38:39], v[148:149], v[154:155], v[38:39] op_sel_hi:[1,0,1] neg_lo:[0,0,1] neg_hi:[0,0,1]
	v_cndmask_b32_e64 v42, v42, v34, s[64:65]
	v_pk_fma_f32 v[28:29], v[28:29], v[142:143], v[36:37]
	v_pk_fma_f32 v[30:31], v[30:31], v[144:145], v[38:39]
	v_cndmask_b32_e64 v43, v43, v35, s[64:65]
	ds_read_b32 v130, v95 offset:17600
	s_waitcnt lgkmcnt(6)
	v_pk_mul_f32 v[24:25], v[30:31], v[52:53]
	v_pk_mul_f32 v[26:27], v[30:31], v[100:101]
	v_pk_fma_f32 v[24:25], v[28:29], v[50:51], v[24:25]
	v_pk_fma_f32 v[26:27], v[28:29], v[98:99], v[26:27]
	ds_read_b128 v[134:137], v94 offset:17680
	v_add_f32_e32 v34, v24, v25
	v_add_f32_e32 v35, v26, v27
	ds_read_b128 v[150:153], v94 offset:18704
	v_add_f32_dpp v34, v34, v34 quad_perm:[1,0,3,2] row_mask:0xf bank_mask:0xf bound_ctrl:1
	v_add_f32_dpp v35, v35, v35 quad_perm:[1,0,3,2] row_mask:0xf bank_mask:0xf bound_ctrl:1
	ds_read_b128 v[138:141], v94 offset:17936
	v_add_f32_dpp v34, v34, v34 quad_perm:[2,3,0,1] row_mask:0xf bank_mask:0xf bound_ctrl:1
	v_add_f32_dpp v35, v35, v35 quad_perm:[2,3,0,1] row_mask:0xf bank_mask:0xf bound_ctrl:1
	ds_read_b128 v[142:145], v94 offset:18192
	v_add_f32_dpp v34, v34, v34 row_ror:4 row_mask:0xf bank_mask:0xf bound_ctrl:1
	v_add_f32_dpp v35, v35, v35 row_ror:4 row_mask:0xf bank_mask:0xf bound_ctrl:1
	ds_read_b128 v[146:149], v94 offset:18448
	v_add_f32_dpp v34, v34, v34 row_ror:8 row_mask:0xf bank_mask:0xf bound_ctrl:1
	v_add_f32_dpp v35, v35, v35 row_ror:8 row_mask:0xf bank_mask:0xf bound_ctrl:1
	v_pk_mul_f32 v[36:37], v[54:55], v[34:35] op_sel_hi:[1,0]
	v_pk_mul_f32 v[38:39], v[56:57], v[34:35] op_sel_hi:[1,0]
	v_pk_fma_f32 v[36:37], v[62:63], v[66:67], v[36:37] op_sel_hi:[1,0,1] neg_lo:[0,0,1] neg_hi:[0,0,1]
	v_pk_fma_f32 v[38:39], v[64:65], v[66:67], v[38:39] op_sel_hi:[1,0,1] neg_lo:[0,0,1] neg_hi:[0,0,1]
	v_cndmask_b32_e64 v42, v42, v34, s[66:67]
	v_pk_fma_f32 v[28:29], v[28:29], v[58:59], v[36:37]
	v_pk_fma_f32 v[30:31], v[30:31], v[60:61], v[38:39]
	v_cndmask_b32_e64 v43, v43, v35, s[66:67]
	ds_read_b32 v154, v95 offset:18960
	s_waitcnt lgkmcnt(6)
	v_pk_mul_f32 v[24:25], v[30:31], v[112:113]
	v_pk_mul_f32 v[26:27], v[30:31], v[128:129]
	v_pk_fma_f32 v[24:25], v[28:29], v[110:111], v[24:25]
	v_pk_fma_f32 v[26:27], v[28:29], v[126:127], v[26:27]
	ds_read_b128 v[50:53], v94 offset:19040
	v_add_f32_e32 v34, v24, v25
	v_add_f32_e32 v35, v26, v27
	ds_read_b128 v[98:101], v94 offset:20064
	v_add_f32_dpp v34, v34, v34 quad_perm:[1,0,3,2] row_mask:0xf bank_mask:0xf bound_ctrl:1
	v_add_f32_dpp v35, v35, v35 quad_perm:[1,0,3,2] row_mask:0xf bank_mask:0xf bound_ctrl:1
	ds_read_b128 v[54:57], v94 offset:19296
	v_add_f32_dpp v34, v34, v34 quad_perm:[2,3,0,1] row_mask:0xf bank_mask:0xf bound_ctrl:1
	v_add_f32_dpp v35, v35, v35 quad_perm:[2,3,0,1] row_mask:0xf bank_mask:0xf bound_ctrl:1
	ds_read_b128 v[58:61], v94 offset:19552
	v_add_f32_dpp v34, v34, v34 row_ror:4 row_mask:0xf bank_mask:0xf bound_ctrl:1
	v_add_f32_dpp v35, v35, v35 row_ror:4 row_mask:0xf bank_mask:0xf bound_ctrl:1
	ds_read_b128 v[62:65], v94 offset:19808
	v_add_f32_dpp v34, v34, v34 row_ror:8 row_mask:0xf bank_mask:0xf bound_ctrl:1
	v_add_f32_dpp v35, v35, v35 row_ror:8 row_mask:0xf bank_mask:0xf bound_ctrl:1
	v_pk_mul_f32 v[36:37], v[114:115], v[34:35] op_sel_hi:[1,0]
	v_pk_mul_f32 v[38:39], v[116:117], v[34:35] op_sel_hi:[1,0]
	v_pk_fma_f32 v[36:37], v[122:123], v[130:131], v[36:37] op_sel_hi:[1,0,1] neg_lo:[0,0,1] neg_hi:[0,0,1]
	v_pk_fma_f32 v[38:39], v[124:125], v[130:131], v[38:39] op_sel_hi:[1,0,1] neg_lo:[0,0,1] neg_hi:[0,0,1]
	v_cndmask_b32_e64 v42, v42, v34, s[68:69]
	v_pk_fma_f32 v[28:29], v[28:29], v[118:119], v[36:37]
	v_pk_fma_f32 v[30:31], v[30:31], v[120:121], v[38:39]
	v_cndmask_b32_e64 v43, v43, v35, s[68:69]
	ds_read_b32 v66, v95 offset:20320
	s_waitcnt lgkmcnt(6)
	v_pk_mul_f32 v[24:25], v[30:31], v[136:137]
	v_pk_mul_f32 v[26:27], v[30:31], v[152:153]
	v_pk_fma_f32 v[24:25], v[28:29], v[134:135], v[24:25]
	v_pk_fma_f32 v[26:27], v[28:29], v[150:151], v[26:27]
	ds_read_b128 v[110:113], v94 offset:20400
	v_add_f32_e32 v34, v24, v25
	v_add_f32_e32 v35, v26, v27
	ds_read_b128 v[126:129], v94 offset:21424
	v_add_f32_dpp v34, v34, v34 quad_perm:[1,0,3,2] row_mask:0xf bank_mask:0xf bound_ctrl:1
	v_add_f32_dpp v35, v35, v35 quad_perm:[1,0,3,2] row_mask:0xf bank_mask:0xf bound_ctrl:1
	ds_read_b128 v[114:117], v94 offset:20656
	v_add_f32_dpp v34, v34, v34 quad_perm:[2,3,0,1] row_mask:0xf bank_mask:0xf bound_ctrl:1
	v_add_f32_dpp v35, v35, v35 quad_perm:[2,3,0,1] row_mask:0xf bank_mask:0xf bound_ctrl:1
	ds_read_b128 v[118:121], v94 offset:20912
	v_add_f32_dpp v34, v34, v34 row_ror:4 row_mask:0xf bank_mask:0xf bound_ctrl:1
	v_add_f32_dpp v35, v35, v35 row_ror:4 row_mask:0xf bank_mask:0xf bound_ctrl:1
	ds_read_b128 v[122:125], v94 offset:21168
	v_add_f32_dpp v34, v34, v34 row_ror:8 row_mask:0xf bank_mask:0xf bound_ctrl:1
	v_add_f32_dpp v35, v35, v35 row_ror:8 row_mask:0xf bank_mask:0xf bound_ctrl:1
	v_pk_mul_f32 v[36:37], v[138:139], v[34:35] op_sel_hi:[1,0]
	v_pk_mul_f32 v[38:39], v[140:141], v[34:35] op_sel_hi:[1,0]
	v_pk_fma_f32 v[36:37], v[146:147], v[154:155], v[36:37] op_sel_hi:[1,0,1] neg_lo:[0,0,1] neg_hi:[0,0,1]
	v_pk_fma_f32 v[38:39], v[148:149], v[154:155], v[38:39] op_sel_hi:[1,0,1] neg_lo:[0,0,1] neg_hi:[0,0,1]
	v_cndmask_b32_e64 v42, v42, v34, s[76:77]
	v_pk_fma_f32 v[28:29], v[28:29], v[142:143], v[36:37]
	v_pk_fma_f32 v[30:31], v[30:31], v[144:145], v[38:39]
	v_cndmask_b32_e64 v43, v43, v35, s[76:77]
	ds_read_b32 v130, v95 offset:21680
	s_waitcnt lgkmcnt(6)
	v_pk_mul_f32 v[24:25], v[30:31], v[52:53]
	v_pk_mul_f32 v[26:27], v[30:31], v[100:101]
	v_pk_fma_f32 v[24:25], v[28:29], v[50:51], v[24:25]
	v_pk_fma_f32 v[26:27], v[28:29], v[98:99], v[26:27]
	v_add_f32_e32 v34, v24, v25
	v_add_f32_e32 v35, v26, v27
	v_lshl_add_u64 v[70:71], v[70:71], 0, s[2:3]
	v_add_f32_dpp v34, v34, v34 quad_perm:[1,0,3,2] row_mask:0xf bank_mask:0xf bound_ctrl:1
	v_add_f32_dpp v35, v35, v35 quad_perm:[1,0,3,2] row_mask:0xf bank_mask:0xf bound_ctrl:1
	v_lshl_add_u64 v[72:73], v[72:73], 0, s[20:21]
	v_add_f32_dpp v34, v34, v34 quad_perm:[2,3,0,1] row_mask:0xf bank_mask:0xf bound_ctrl:1
	v_add_f32_dpp v35, v35, v35 quad_perm:[2,3,0,1] row_mask:0xf bank_mask:0xf bound_ctrl:1
	v_lshl_add_u64 v[74:75], v[74:75], 0, s[20:21]
	v_add_f32_dpp v34, v34, v34 row_ror:4 row_mask:0xf bank_mask:0xf bound_ctrl:1
	v_add_f32_dpp v35, v35, v35 row_ror:4 row_mask:0xf bank_mask:0xf bound_ctrl:1
	s_nop 0
	v_add_f32_dpp v34, v34, v34 row_ror:8 row_mask:0xf bank_mask:0xf bound_ctrl:1
	v_add_f32_dpp v35, v35, v35 row_ror:8 row_mask:0xf bank_mask:0xf bound_ctrl:1
	v_pk_mul_f32 v[36:37], v[54:55], v[34:35] op_sel_hi:[1,0]
	v_pk_mul_f32 v[38:39], v[56:57], v[34:35] op_sel_hi:[1,0]
	v_pk_fma_f32 v[36:37], v[62:63], v[66:67], v[36:37] op_sel_hi:[1,0,1] neg_lo:[0,0,1] neg_hi:[0,0,1]
	v_pk_fma_f32 v[38:39], v[64:65], v[66:67], v[38:39] op_sel_hi:[1,0,1] neg_lo:[0,0,1] neg_hi:[0,0,1]
	v_cndmask_b32_e32 v42, v42, v34, vcc
	v_pk_fma_f32 v[28:29], v[28:29], v[58:59], v[36:37]
	v_pk_fma_f32 v[30:31], v[30:31], v[60:61], v[38:39]
	v_cndmask_b32_e32 v43, v43, v35, vcc
	s_waitcnt lgkmcnt(0)
	v_pk_mul_f32 v[24:25], v[30:31], v[112:113]
	v_pk_mul_f32 v[26:27], v[30:31], v[128:129]
	v_pk_fma_f32 v[24:25], v[28:29], v[110:111], v[24:25]
	v_pk_fma_f32 v[26:27], v[28:29], v[126:127], v[26:27]
	v_add_f32_e32 v34, v24, v25
	v_add_f32_e32 v35, v26, v27
	v_lshl_add_u64 v[32:33], v[68:69], 0, s[0:1]
	v_add_f32_dpp v34, v34, v34 quad_perm:[1,0,3,2] row_mask:0xf bank_mask:0xf bound_ctrl:1
	v_add_f32_dpp v35, v35, v35 quad_perm:[1,0,3,2] row_mask:0xf bank_mask:0xf bound_ctrl:1
	s_nop 0
	v_add_f32_dpp v34, v34, v34 quad_perm:[2,3,0,1] row_mask:0xf bank_mask:0xf bound_ctrl:1
	v_add_f32_dpp v35, v35, v35 quad_perm:[2,3,0,1] row_mask:0xf bank_mask:0xf bound_ctrl:1
	s_nop 0
	v_add_f32_dpp v34, v34, v34 row_ror:4 row_mask:0xf bank_mask:0xf bound_ctrl:1
	v_add_f32_dpp v35, v35, v35 row_ror:4 row_mask:0xf bank_mask:0xf bound_ctrl:1
	s_nop 0
	v_add_f32_dpp v34, v34, v34 row_ror:8 row_mask:0xf bank_mask:0xf bound_ctrl:1
	v_add_f32_dpp v35, v35, v35 row_ror:8 row_mask:0xf bank_mask:0xf bound_ctrl:1
	v_pk_mul_f32 v[36:37], v[114:115], v[34:35] op_sel_hi:[1,0]
	v_pk_mul_f32 v[38:39], v[116:117], v[34:35] op_sel_hi:[1,0]
	v_pk_fma_f32 v[36:37], v[122:123], v[130:131], v[36:37] op_sel_hi:[1,0,1] neg_lo:[0,0,1] neg_hi:[0,0,1]
	v_pk_fma_f32 v[38:39], v[124:125], v[130:131], v[38:39] op_sel_hi:[1,0,1] neg_lo:[0,0,1] neg_hi:[0,0,1]
	v_cndmask_b32_e64 v42, v42, v34, s[4:5]
	v_pk_fma_f32 v[28:29], v[28:29], v[118:119], v[36:37]
	v_pk_fma_f32 v[30:31], v[30:31], v[120:121], v[38:39]
	v_cndmask_b32_e64 v43, v43, v35, s[4:5]
	s_add_u32 s0, s0, 0x1000
	s_addc_u32 s1, s1, 0
	s_mov_b32 s24, s38
	v_fma_f32 v40, -v44, v42, v43
	s_cmp_lg_u32 s0, 0x54000
	v_fmac_f32_e32 v40, v48, v45
	global_store_dword v[32:33], v40, off
	s_barrier
	s_cbranch_scc0 .LBB0_233
